# EpiResid: all 32 read-once f32 residual loads per epilogue issued nt (was 38 of 128)
# speedup vs baseline: 1.0090x; 1.0037x over previous
; #define PG8_STAGE(bufoff, gbase, voff) do { _Pragma("unroll") for (int _i = 0; _i < 2; ++_i) \
;         __builtin_amdgcn_global_load_lds((const unsigned*)((const char*)(gbase) + (voff)[_i]), (LAS unsigned*)(lds + (bufoff) + ldsw + _i * 8192), 16, 0, 0); } while (0)
; #define PG8_LDA(dst, b, h) do { _Pragma("unroll") for (int m = 0; m < 4; ++m) _Pragma("unroll") for (int k = 0; k < 2; ++k) dst[m][k] = *(const LAS bf16x8*)(lds + PG8_SA(b, h) + aoff + m * 2048 + k * 1024); } while (0)
; #define PG8_LDB(dst, b, h) do { _Pragma("unroll") for (int n = 0; n < 2; ++n) _Pragma("unroll") for (int k = 0; k < 2; ++k) dst[n][k] = *(const LAS bf16x8*)(lds + PG8_SB(b, h) + boff + n * 2048 + k * 1024); } while (0)
; #define PG8_MMA(ai, bj, At, Bt) do { __builtin_amdgcn_s_setprio(1); _Pragma("unroll") for (int m = 0; m < 4; ++m) _Pragma("unroll") for (int n = 0; n < 2; ++n) _Pragma("unroll") for (int k = 0; k < 2; ++k) \
;         acc[ai][bj][m][n] = __builtin_amdgcn_mfma_f32_16x16x32_bf16(Bt[n][k], At[m][k], acc[ai][bj][m][n], 0, 0, 0); __builtin_amdgcn_s_setprio(0); } while (0)
; #define PG8_WAIT_L(n) asm volatile("s_waitcnt lgkmcnt(" #n ")" ::: "memory")
; #define PG8_BAR __builtin_amdgcn_s_barrier()
; #define PG8_SCHED __builtin_amdgcn_sched_barrier(0)
; template <class Epi>
; DEVI void gemm_phase(LAS unsigned char* lds, const Gemm g, const Epi& E) {
;     ...
;         for (int t = 0; t < nt; t += 2) {
;             const bool last = (t == nt - 2);
;             const char* a1 = cA + (size_t)(t + 1) * kstep;
;             const char* a2 = last ? nA : cA + (size_t)(t + 2) * kstep; const char* b2 = last ? nB : cB + (size_t)(t + 2) * kstep;
;             const char* a3 = a2 + kstep; const char* b3 = b2 + kstep;
;             PG8_LDB(B0, 0, 0); PG8_SCHED; PG8_LDA(At, 0, 0); PG8_STAGE(PG8_SA(1, 1), a1 + hstepA, voffA);
;             PG8_WAIT_L(8); PG8_BAR; PG8_WAIT_L(0); PG8_MMA(0, 0, At, B0); PG8_BAR; PG8_SCHED;
;             PG8_LDB(B1, 0, 1); PG8_STAGE(PG8_SB(0, 0), b2, voffB);
;             PG8_BAR; PG8_WAIT_L(0); PG8_MMA(0, 1, At, B1); PG8_BAR;
;             PG8_LDA(At, 0, 1); PG8_STAGE(PG8_SA(0, 0), a2, voffA);
;             PG8_BAR; PG8_WAIT_L(0); PG8_MMA(1, 0, At, B0); PG8_BAR; PG8_SCHED;
.LBB0_968:
	s_add_u32 s26, s68, 0xfffc0080
	s_addc_u32 s27, s69, -1
	s_add_i32 s38, 0, 0x10000
	v_add_u32_e32 v142, s38, v193
	ds_read_b128 v[130:133], v142
	ds_read_b128 v[134:137], v142 offset:1024
	ds_read_b128 v[138:141], v142 offset:2048
	ds_read_b128 v[142:145], v142 offset:3072
	s_cmp_eq_u32 s19, 12
	s_cselect_b32 s83, s0, s27
	s_cselect_b32 s82, s1, s26
	s_cselect_b32 s81, s9, s18
	s_cselect_b32 s80, s13, s15
	v_lshl_add_u64 v[162:163], s[68:69], 0, v[178:179]
	s_add_i32 m0, s85, 0xc000
	ds_read_b128 v[146:149], v198
	ds_read_b128 v[182:185], v198 offset:1024
	ds_read_b128 v[186:189], v198 offset:2048
	ds_read_b128 v[200:203], v198 offset:3072
	ds_read_b128 v[204:207], v198 offset:4096
	ds_read_b128 v[214:217], v198 offset:5120
	ds_read_b128 v[218:221], v198 offset:6144
	ds_read_b128 v[222:225], v198 offset:7168
	global_load_lds_dwordx4 v[162:163], off
	s_add_i32 m0, s85, 0xe000
	v_lshl_add_u64 v[162:163], s[68:69], 0, v[180:181]
	global_load_lds_dwordx4 v[162:163], off
	s_waitcnt lgkmcnt(8)
	s_barrier
	s_waitcnt lgkmcnt(0)
	v_mfma_f32_16x16x32_bf16 v[126:129], v[130:133], v[146:149], v[126:129]
	v_mfma_f32_16x16x32_bf16 v[122:125], v[138:141], v[146:149], v[122:125]
	v_mfma_f32_16x16x32_bf16 v[110:113], v[130:133], v[186:189], v[110:113]
	v_mfma_f32_16x16x32_bf16 v[106:109], v[138:141], v[186:189], v[106:109]
	v_mfma_f32_16x16x32_bf16 v[94:97], v[130:133], v[204:207], v[94:97]
	v_mfma_f32_16x16x32_bf16 v[90:93], v[138:141], v[204:207], v[90:93]
	v_mfma_f32_16x16x32_bf16 v[78:81], v[130:133], v[218:221], v[78:81]
	v_mfma_f32_16x16x32_bf16 v[74:77], v[138:141], v[218:221], v[74:77]
	v_mfma_f32_16x16x32_bf16 v[126:129], v[134:137], v[182:185], v[126:129]
	v_mfma_f32_16x16x32_bf16 v[122:125], v[142:145], v[182:185], v[122:125]
	v_mfma_f32_16x16x32_bf16 v[110:113], v[134:137], v[200:203], v[110:113]
	v_mfma_f32_16x16x32_bf16 v[106:109], v[142:145], v[200:203], v[106:109]
	v_mfma_f32_16x16x32_bf16 v[94:97], v[134:137], v[214:217], v[94:97]
	v_mfma_f32_16x16x32_bf16 v[90:93], v[142:145], v[214:217], v[90:93]
	v_mfma_f32_16x16x32_bf16 v[78:81], v[134:137], v[222:225], v[78:81]
	v_mfma_f32_16x16x32_bf16 v[74:77], v[142:145], v[222:225], v[74:77]
	s_barrier
	s_add_i32 s39, 0, 0x14000
	v_add_u32_e32 v162, s39, v193
	s_add_i32 s26, s38, s84
	ds_read_b128 v[226:229], v162
	ds_read_b128 v[230:233], v162 offset:1024
	ds_read_b128 v[234:237], v162 offset:2048
	ds_read_b128 v[238:241], v162 offset:3072
	v_lshl_add_u64 v[162:163], s[80:81], 0, v[8:9]
	s_mov_b32 m0, s26
	v_lshl_add_u64 v[164:165], s[80:81], 0, v[176:177]
	global_load_lds_dwordx4 v[162:163], off
	s_add_i32 m0, s26, 0x2000
	s_nop 0
	global_load_lds_dwordx4 v[164:165], off
	s_barrier
	s_waitcnt lgkmcnt(0)
	v_mfma_f32_16x16x32_bf16 v[118:121], v[226:229], v[146:149], v[118:121]
	v_mfma_f32_16x16x32_bf16 v[114:117], v[234:237], v[146:149], v[114:117]
	v_mfma_f32_16x16x32_bf16 v[102:105], v[226:229], v[186:189], v[102:105]
	v_mfma_f32_16x16x32_bf16 v[98:101], v[234:237], v[186:189], v[98:101]
	v_mfma_f32_16x16x32_bf16 v[86:89], v[226:229], v[204:207], v[86:89]
	v_mfma_f32_16x16x32_bf16 v[82:85], v[234:237], v[204:207], v[82:85]
	v_mfma_f32_16x16x32_bf16 v[70:73], v[226:229], v[218:221], v[70:73]
	v_mfma_f32_16x16x32_bf16 v[66:69], v[234:237], v[218:221], v[66:69]
	v_mfma_f32_16x16x32_bf16 v[118:121], v[230:233], v[182:185], v[118:121]
	v_mfma_f32_16x16x32_bf16 v[114:117], v[238:241], v[182:185], v[114:117]
	v_mfma_f32_16x16x32_bf16 v[102:105], v[230:233], v[200:203], v[102:105]
	v_mfma_f32_16x16x32_bf16 v[98:101], v[238:241], v[200:203], v[98:101]
	v_mfma_f32_16x16x32_bf16 v[86:89], v[230:233], v[214:217], v[86:89]
	v_mfma_f32_16x16x32_bf16 v[82:85], v[238:241], v[214:217], v[82:85]
	v_mfma_f32_16x16x32_bf16 v[70:73], v[230:233], v[222:225], v[70:73]
	v_mfma_f32_16x16x32_bf16 v[66:69], v[238:241], v[222:225], v[66:69]
	s_mov_b32 m0, s85
	v_lshl_add_u64 v[190:191], s[82:83], 0, v[150:151]
	s_barrier
	ds_read_b128 v[146:149], v198 offset:16384
	ds_read_b128 v[182:185], v198 offset:17408
	ds_read_b128 v[186:189], v198 offset:18432
	ds_read_b128 v[200:203], v198 offset:19456
	ds_read_b128 v[204:207], v198 offset:20480
	ds_read_b128 v[214:217], v198 offset:21504
	ds_read_b128 v[218:221], v198 offset:22528
	ds_read_b128 v[222:225], v198 offset:23552
	global_load_lds_dwordx4 v[190:191], off
	s_mov_b32 m0, s86
	v_lshl_add_u64 v[208:209], s[82:83], 0, v[152:153]
	global_load_lds_dwordx4 v[208:209], off
	s_barrier
	s_waitcnt lgkmcnt(0)
	v_mfma_f32_16x16x32_bf16 v[62:65], v[130:133], v[146:149], v[62:65]
	v_mfma_f32_16x16x32_bf16 v[58:61], v[138:141], v[146:149], v[58:61]
	v_mfma_f32_16x16x32_bf16 v[46:49], v[130:133], v[186:189], v[46:49]
	v_mfma_f32_16x16x32_bf16 v[42:45], v[138:141], v[186:189], v[42:45]
	v_mfma_f32_16x16x32_bf16 v[30:33], v[130:133], v[204:207], v[30:33]
	v_mfma_f32_16x16x32_bf16 v[26:29], v[138:141], v[204:207], v[26:29]
	v_mfma_f32_16x16x32_bf16 v[14:17], v[130:133], v[218:221], v[14:17]
	v_mfma_f32_16x16x32_bf16 v[10:13], v[138:141], v[218:221], v[10:13]
	v_mfma_f32_16x16x32_bf16 v[62:65], v[134:137], v[182:185], v[62:65]
	v_mfma_f32_16x16x32_bf16 v[58:61], v[142:145], v[182:185], v[58:61]
	v_mfma_f32_16x16x32_bf16 v[46:49], v[134:137], v[200:203], v[46:49]
	v_mfma_f32_16x16x32_bf16 v[42:45], v[142:145], v[200:203], v[42:45]
	v_mfma_f32_16x16x32_bf16 v[30:33], v[134:137], v[214:217], v[30:33]
	v_mfma_f32_16x16x32_bf16 v[26:29], v[142:145], v[214:217], v[26:29]
	v_mfma_f32_16x16x32_bf16 v[14:17], v[134:137], v[222:225], v[14:17]
	v_mfma_f32_16x16x32_bf16 v[10:13], v[142:145], v[222:225], v[10:13]
	s_barrier
; #define PG8_STAGE(bufoff, gbase, voff) do { _Pragma("unroll") for (int _i = 0; _i < 2; ++_i) \
;         __builtin_amdgcn_global_load_lds((const unsigned*)((const char*)(gbase) + (voff)[_i]), (LAS unsigned*)(lds + (bufoff) + ldsw + _i * 8192), 16, 0, 0); } while (0)
; #define PG8_LDA(dst, b, h) do { _Pragma("unroll") for (int m = 0; m < 4; ++m) _Pragma("unroll") for (int k = 0; k < 2; ++k) dst[m][k] = *(const LAS bf16x8*)(lds + PG8_SA(b, h) + aoff + m * 2048 + k * 1024); } while (0)
; #define PG8_LDB(dst, b, h) do { _Pragma("unroll") for (int n = 0; n < 2; ++n) _Pragma("unroll") for (int k = 0; k < 2; ++k) dst[n][k] = *(const LAS bf16x8*)(lds + PG8_SB(b, h) + boff + n * 2048 + k * 1024); } while (0)
; #define PG8_MMA(ai, bj, At, Bt) do { __builtin_amdgcn_s_setprio(1); _Pragma("unroll") for (int m = 0; m < 4; ++m) _Pragma("unroll") for (int n = 0; n < 2; ++n) _Pragma("unroll") for (int k = 0; k < 2; ++k) \
;         acc[ai][bj][m][n] = __builtin_amdgcn_mfma_f32_16x16x32_bf16(Bt[n][k], At[m][k], acc[ai][bj][m][n], 0, 0, 0); __builtin_amdgcn_s_setprio(0); } while (0)
; #define PG8_WAIT_V(n) asm volatile("s_waitcnt vmcnt(" #n ")" ::: "memory")
; #define PG8_WAIT_L(n) asm volatile("s_waitcnt lgkmcnt(" #n ")" ::: "memory")
; #define PG8_BAR __builtin_amdgcn_s_barrier()
; #define PG8_SCHED __builtin_amdgcn_sched_barrier(0)
; template <class Epi>
; DEVI void gemm_phase(LAS unsigned char* lds, const Gemm g, const Epi& E) {
;     ...
;             PG8_STAGE(PG8_SB(0, 1), b2 + hstepB, voffB);
;             PG8_WAIT_V(6); PG8_BAR; PG8_MMA(1, 1, At, B1); PG8_BAR;
;             PG8_LDB(B0, 1, 0); PG8_SCHED; PG8_LDA(At, 1, 0); PG8_STAGE(PG8_SA(0, 1), a2 + hstepA, voffA);
;             PG8_WAIT_L(8); PG8_BAR; PG8_WAIT_L(0); PG8_MMA(0, 0, At, B0); PG8_BAR; PG8_SCHED;
;             PG8_LDB(B1, 1, 1); PG8_STAGE(PG8_SB(1, 0), b3, voffB);
;             PG8_BAR; PG8_WAIT_L(0); PG8_MMA(0, 1, At, B1); PG8_BAR;
;             PG8_LDA(At, 1, 1); PG8_STAGE(PG8_SA(1, 0), a3, voffA);
;             PG8_BAR; PG8_WAIT_L(0); PG8_MMA(1, 0, At, B0); PG8_BAR; PG8_SCHED;
;             PG8_STAGE(PG8_SB(1, 1), b3 + hstepB, voffB);
;             PG8_WAIT_V(6); PG8_BAR; PG8_MMA(1, 1, At, B1); PG8_BAR;
	s_add_u32 s26, s80, 0x40000
	s_addc_u32 s27, s81, 0
	s_add_i32 s38, s39, s84
	s_mov_b32 m0, s38
	v_lshl_add_u64 v[130:131], s[26:27], 0, v[8:9]
	global_load_lds_dwordx4 v[130:131], off
	s_add_i32 m0, s38, 0x2000
	v_lshl_add_u64 v[130:131], s[26:27], 0, v[176:177]
	global_load_lds_dwordx4 v[130:131], off
	s_waitcnt vmcnt(6)
	s_barrier
	v_mfma_f32_16x16x32_bf16 v[54:57], v[226:229], v[146:149], v[54:57]
	v_mfma_f32_16x16x32_bf16 v[50:53], v[234:237], v[146:149], v[50:53]
	v_mfma_f32_16x16x32_bf16 v[38:41], v[226:229], v[186:189], v[38:41]
	v_mfma_f32_16x16x32_bf16 v[34:37], v[234:237], v[186:189], v[34:37]
	v_mfma_f32_16x16x32_bf16 v[22:25], v[226:229], v[204:207], v[22:25]
	v_mfma_f32_16x16x32_bf16 v[18:21], v[234:237], v[204:207], v[18:21]
	v_mfma_f32_16x16x32_bf16 v[4:7], v[226:229], v[218:221], v[4:7]
	v_mfma_f32_16x16x32_bf16 v[0:3], v[234:237], v[218:221], v[0:3]
	v_mfma_f32_16x16x32_bf16 v[54:57], v[230:233], v[182:185], v[54:57]
	v_mfma_f32_16x16x32_bf16 v[50:53], v[238:241], v[182:185], v[50:53]
	v_mfma_f32_16x16x32_bf16 v[38:41], v[230:233], v[200:203], v[38:41]
	v_mfma_f32_16x16x32_bf16 v[34:37], v[238:241], v[200:203], v[34:37]
	v_mfma_f32_16x16x32_bf16 v[22:25], v[230:233], v[214:217], v[22:25]
	v_mfma_f32_16x16x32_bf16 v[18:21], v[238:241], v[214:217], v[18:21]
	v_mfma_f32_16x16x32_bf16 v[4:7], v[230:233], v[222:225], v[4:7]
	v_mfma_f32_16x16x32_bf16 v[0:3], v[238:241], v[222:225], v[0:3]
	s_add_i32 s38, 0, 0x18000
	v_add_u32_e32 v142, s38, v193
	s_barrier
	ds_read_b128 v[130:133], v142
	ds_read_b128 v[134:137], v142 offset:1024
	ds_read_b128 v[138:141], v142 offset:2048
	ds_read_b128 v[142:145], v142 offset:3072
	s_add_u32 s26, s82, 0x40000
	s_addc_u32 s27, s83, 0
	s_mov_b32 m0, s87
	v_lshl_add_u64 v[226:227], s[26:27], 0, v[150:151]
	ds_read_b128 v[146:149], v198 offset:32768
	ds_read_b128 v[182:185], v198 offset:33792
	ds_read_b128 v[186:189], v198 offset:34816
	ds_read_b128 v[200:203], v198 offset:35840
	ds_read_b128 v[204:207], v198 offset:36864
	ds_read_b128 v[214:217], v198 offset:37888
	ds_read_b128 v[218:221], v198 offset:38912
	ds_read_b128 v[222:225], v198 offset:39936
	global_load_lds_dwordx4 v[226:227], off
	s_mov_b32 m0, s88
	v_lshl_add_u64 v[226:227], s[26:27], 0, v[152:153]
	global_load_lds_dwordx4 v[226:227], off
	s_waitcnt lgkmcnt(8)
	s_barrier
	s_waitcnt lgkmcnt(0)
	v_mfma_f32_16x16x32_bf16 v[126:129], v[130:133], v[146:149], v[126:129]
	v_mfma_f32_16x16x32_bf16 v[122:125], v[138:141], v[146:149], v[122:125]
	v_mfma_f32_16x16x32_bf16 v[110:113], v[130:133], v[186:189], v[110:113]
	v_mfma_f32_16x16x32_bf16 v[106:109], v[138:141], v[186:189], v[106:109]
	v_mfma_f32_16x16x32_bf16 v[94:97], v[130:133], v[204:207], v[94:97]
	v_mfma_f32_16x16x32_bf16 v[90:93], v[138:141], v[204:207], v[90:93]
	v_mfma_f32_16x16x32_bf16 v[78:81], v[130:133], v[218:221], v[78:81]
	v_mfma_f32_16x16x32_bf16 v[74:77], v[138:141], v[218:221], v[74:77]
	v_mfma_f32_16x16x32_bf16 v[126:129], v[134:137], v[182:185], v[126:129]
	v_mfma_f32_16x16x32_bf16 v[122:125], v[142:145], v[182:185], v[122:125]
	v_mfma_f32_16x16x32_bf16 v[110:113], v[134:137], v[200:203], v[110:113]
	v_mfma_f32_16x16x32_bf16 v[106:109], v[142:145], v[200:203], v[106:109]
	v_mfma_f32_16x16x32_bf16 v[94:97], v[134:137], v[214:217], v[94:97]
	v_mfma_f32_16x16x32_bf16 v[90:93], v[142:145], v[214:217], v[90:93]
	v_mfma_f32_16x16x32_bf16 v[78:81], v[134:137], v[222:225], v[78:81]
	v_mfma_f32_16x16x32_bf16 v[74:77], v[142:145], v[222:225], v[74:77]
	s_barrier
	s_add_i32 s39, 0, 0x1c000
	s_add_i32 s26, s38, s84
	v_add_u32_e32 v199, s39, v193
	v_lshl_add_u64 v[162:163], v[162:163], 0, s[70:71]
	s_mov_b32 m0, s26
	ds_read_b128 v[226:229], v199
	ds_read_b128 v[230:233], v199 offset:1024
	ds_read_b128 v[234:237], v199 offset:2048
	ds_read_b128 v[238:241], v199 offset:3072
	global_load_lds_dwordx4 v[162:163], off
	s_add_i32 m0, s26, 0x2000
	v_lshl_add_u64 v[162:163], v[164:165], 0, s[70:71]
	global_load_lds_dwordx4 v[162:163], off
	s_barrier
	s_waitcnt lgkmcnt(0)
	v_mfma_f32_16x16x32_bf16 v[118:121], v[226:229], v[146:149], v[118:121]
	v_mfma_f32_16x16x32_bf16 v[114:117], v[234:237], v[146:149], v[114:117]
	v_mfma_f32_16x16x32_bf16 v[102:105], v[226:229], v[186:189], v[102:105]
	v_mfma_f32_16x16x32_bf16 v[98:101], v[234:237], v[186:189], v[98:101]
	v_mfma_f32_16x16x32_bf16 v[86:89], v[226:229], v[204:207], v[86:89]
	v_mfma_f32_16x16x32_bf16 v[82:85], v[234:237], v[204:207], v[82:85]
	v_mfma_f32_16x16x32_bf16 v[70:73], v[226:229], v[218:221], v[70:73]
	v_mfma_f32_16x16x32_bf16 v[66:69], v[234:237], v[218:221], v[66:69]
	v_mfma_f32_16x16x32_bf16 v[118:121], v[230:233], v[182:185], v[118:121]
	v_mfma_f32_16x16x32_bf16 v[114:117], v[238:241], v[182:185], v[114:117]
	v_mfma_f32_16x16x32_bf16 v[102:105], v[230:233], v[200:203], v[102:105]
	v_mfma_f32_16x16x32_bf16 v[98:101], v[238:241], v[200:203], v[98:101]
	v_mfma_f32_16x16x32_bf16 v[86:89], v[230:233], v[214:217], v[86:89]
	v_mfma_f32_16x16x32_bf16 v[82:85], v[238:241], v[214:217], v[82:85]
	v_mfma_f32_16x16x32_bf16 v[70:73], v[230:233], v[222:225], v[70:73]
	v_mfma_f32_16x16x32_bf16 v[66:69], v[238:241], v[222:225], v[66:69]
	s_mov_b32 m0, s89
	v_lshl_add_u64 v[162:163], v[190:191], 0, s[70:71]
	s_barrier
	ds_read_b128 v[146:149], v198 offset:49152
	ds_read_b128 v[182:185], v198 offset:50176
	ds_read_b128 v[186:189], v198 offset:51200
	ds_read_b128 v[200:203], v198 offset:52224
	ds_read_b128 v[204:207], v198 offset:53248
	ds_read_b128 v[214:217], v198 offset:54272
	ds_read_b128 v[218:221], v198 offset:55296
	ds_read_b128 v[222:225], v198 offset:56320
	global_load_lds_dwordx4 v[162:163], off
	s_mov_b32 m0, s90
	v_lshl_add_u64 v[162:163], v[208:209], 0, s[70:71]
	global_load_lds_dwordx4 v[162:163], off
	s_barrier
; #define LAS __attribute__((address_space(3)))
;     DEVI f32x4 load(int r, int c) const { const bf16x4 y = *(const bf16x4*)(Y + (size_t)r * DM + c); return (f32x4){bf2f((u16)y[0]), bf2f((u16)y[1]), bf2f((u16)y[2]), bf2f((u16)y[3])}; }
; template <class Epi>
; DEVI void gemm_phase(LAS unsigned char* lds, const Gemm g, const Epi& E) {
;     ...
;             for (int am = 0; am < 4; ++am) {
;                 const int ai = am >> 1, m0 = (am & 1) * 2;
;                 f32x4 pre[2][2][2];
;                 if constexpr (Epi::PRE) {
; #pragma unroll
;                     for (int m = 0; m < 2; ++m)
; #pragma unroll
;                         for (int bj = 0; bj < 2; ++bj)
; #pragma unroll
;                             for (int n = 0; n < 2; ++n) pre[m][bj][n] = E.load(row0 + ai * HALF + (m0 + m) * 16, col0 + bj * HALF + n * NST);
;                 }
; #pragma unroll
;                 for (int mm = 0; mm < 2; ++mm) {
;                     const int m = m0 + mm;
;                     const int r = row0 + ai * HALF + m * 16; float rs = 1.f, part = 0.f;
;                     if constexpr (Epi::RS) rs = rsv[ai * 4 + m];
;                     if constexpr (Epi::PAIR) E.pair8(cur.b, r, cur.pn * HALF + wc * 32 + 8 * fq, acc[ai][0][m][0] * rs, acc[ai][0][m][1] * rs, acc[ai][1][m][0] * rs, acc[ai][1][m][1] * rs);
;                     else
; #pragma unroll
;                     for (int bj = 0; bj < 2; ++bj) {
;                         const int c = col0 + bj * HALF; f32x4 v0 = acc[ai][bj][m][0], v1 = acc[ai][bj][m][1];
;                         if constexpr (Epi::RS) { v0 = v0 * rs; v1 = v1 * rs; }
;                         if constexpr (Epi::PRE) part += E.frag_pre8(cur.b, r, c, v0, v1, pre[mm][bj][0], pre[mm][bj][1]);
;                         else if constexpr (Epi::PERM) E.frag8(cur.b, r, c, v0, v1);
;                         else { E.frag(cur.b, r, c, v0); E.frag(cur.b, r, c + 16, v1); }
;                     }
;                     if constexpr (Epi::SSQ) { part += __shfl_xor(part, 16); part += __shfl_xor(part, 32); if (fq == 0) ((LAS float*)(lds + 131072))[(wr * 4 + wc) * 128 + ai * 64 + m * 16 + fr] = part; }
	s_waitcnt lgkmcnt(0)
	v_mfma_f32_16x16x32_bf16 v[62:65], v[130:133], v[146:149], v[62:65]
	v_mfma_f32_16x16x32_bf16 v[58:61], v[138:141], v[146:149], v[58:61]
	v_mfma_f32_16x16x32_bf16 v[46:49], v[130:133], v[186:189], v[46:49]
	v_mfma_f32_16x16x32_bf16 v[42:45], v[138:141], v[186:189], v[42:45]
	v_mfma_f32_16x16x32_bf16 v[30:33], v[130:133], v[204:207], v[30:33]
	v_mfma_f32_16x16x32_bf16 v[26:29], v[138:141], v[204:207], v[26:29]
	v_mfma_f32_16x16x32_bf16 v[14:17], v[130:133], v[218:221], v[14:17]
	v_mfma_f32_16x16x32_bf16 v[10:13], v[138:141], v[218:221], v[10:13]
	v_mfma_f32_16x16x32_bf16 v[62:65], v[134:137], v[182:185], v[62:65]
	v_mfma_f32_16x16x32_bf16 v[58:61], v[142:145], v[182:185], v[58:61]
	v_mfma_f32_16x16x32_bf16 v[46:49], v[134:137], v[200:203], v[46:49]
	v_mfma_f32_16x16x32_bf16 v[42:45], v[142:145], v[200:203], v[42:45]
	v_mfma_f32_16x16x32_bf16 v[30:33], v[134:137], v[214:217], v[30:33]
	v_mfma_f32_16x16x32_bf16 v[26:29], v[142:145], v[214:217], v[26:29]
	v_mfma_f32_16x16x32_bf16 v[14:17], v[134:137], v[222:225], v[14:17]
	v_mfma_f32_16x16x32_bf16 v[10:13], v[142:145], v[222:225], v[10:13]
	s_barrier
	s_add_u32 s26, s80, 0x40080
	s_addc_u32 s27, s81, 0
	s_add_i32 s38, s39, s84
	s_mov_b32 m0, s38
	v_lshl_add_u64 v[130:131], s[26:27], 0, v[8:9]
	global_load_lds_dwordx4 v[130:131], off
	s_add_i32 m0, s38, 0x2000
	v_lshl_add_u64 v[130:131], s[26:27], 0, v[176:177]
	global_load_lds_dwordx4 v[130:131], off
	s_waitcnt vmcnt(6)
	s_barrier
	v_mfma_f32_16x16x32_bf16 v[54:57], v[226:229], v[146:149], v[54:57]
	v_mfma_f32_16x16x32_bf16 v[50:53], v[234:237], v[146:149], v[50:53]
	v_mfma_f32_16x16x32_bf16 v[38:41], v[226:229], v[186:189], v[38:41]
	v_mfma_f32_16x16x32_bf16 v[34:37], v[234:237], v[186:189], v[34:37]
	v_mfma_f32_16x16x32_bf16 v[22:25], v[226:229], v[204:207], v[22:25]
	v_mfma_f32_16x16x32_bf16 v[18:21], v[234:237], v[204:207], v[18:21]
	v_mfma_f32_16x16x32_bf16 v[4:7], v[226:229], v[218:221], v[4:7]
	v_mfma_f32_16x16x32_bf16 v[0:3], v[234:237], v[218:221], v[0:3]
	v_mfma_f32_16x16x32_bf16 v[54:57], v[230:233], v[182:185], v[54:57]
	v_mfma_f32_16x16x32_bf16 v[50:53], v[238:241], v[182:185], v[50:53]
	v_mfma_f32_16x16x32_bf16 v[38:41], v[230:233], v[200:203], v[38:41]
	v_mfma_f32_16x16x32_bf16 v[34:37], v[238:241], v[200:203], v[34:37]
	v_mfma_f32_16x16x32_bf16 v[22:25], v[230:233], v[214:217], v[22:25]
	v_mfma_f32_16x16x32_bf16 v[18:21], v[238:241], v[214:217], v[18:21]
	v_mfma_f32_16x16x32_bf16 v[4:7], v[230:233], v[222:225], v[4:7]
	v_mfma_f32_16x16x32_bf16 v[0:3], v[238:241], v[222:225], v[0:3]
	s_add_i32 s19, s19, 2
	s_add_u32 s68, s68, 0x100
	s_addc_u32 s69, s69, 0
	s_add_u32 s15, s15, 0x100
	s_addc_u32 s18, s18, 0
	s_cmp_gt_u32 s19, 13
	s_barrier
	s_cbranch_scc0 .LBB0_968
	s_setprio 0
	v_and_b32_e32 v131, 64, v155
	v_xor_b32_e32 v130, 16, v155
	v_add_u32_e32 v131, 64, v131
	v_cmp_lt_i32_e32 vcc, v130, v131
	s_lshl_b32 s9, s46, 8
	v_add_u32_e32 v186, s9, v192
	v_cndmask_b32_e32 v130, v155, v130, vcc
	v_lshlrev_b32_e32 v200, 2, v130
	v_xor_b32_e32 v130, 32, v155
	v_cmp_lt_i32_e32 vcc, v130, v131
	v_lshl_or_b32 v184, s8, 8, v197
	v_ashrrev_i32_e32 v187, 31, v186
	v_cndmask_b32_e32 v130, v155, v130, vcc
	v_lshlrev_b32_e32 v199, 2, v130
	v_lshlrev_b64 v[130:131], 12, v[186:187]
	v_ashrrev_i32_e32 v185, 31, v184
	v_lshl_add_u64 v[130:131], s[78:79], 0, v[130:131]
	v_lshlrev_b64 v[188:189], 2, v[184:185]
	v_lshl_add_u64 v[130:131], v[130:131], 0, v[188:189]
	global_load_dwordx4 v[202:205], v[130:131], off offset:16 nt
	global_load_dwordx4 v[206:209], v[130:131], off nt
	global_load_dwordx4 v[146:149], v[130:131], off offset:528 nt
	global_load_dwordx4 v[214:217], v[130:131], off offset:512 nt
	v_or_b32_e32 v190, 16, v186
	v_ashrrev_i32_e32 v191, 31, v190
	v_lshlrev_b64 v[130:131], 12, v[190:191]
	v_lshl_add_u64 v[130:131], s[78:79], 0, v[130:131]
	v_lshl_add_u64 v[134:135], v[130:131], 0, v[188:189]
	global_load_dwordx4 v[138:141], v[134:135], off offset:16 nt
	global_load_dwordx4 v[142:145], v[134:135], off nt
	global_load_dwordx4 v[130:133], v[134:135], off offset:528 nt
	s_nop 0
	global_load_dwordx4 v[134:137], v[134:135], off offset:512 nt
	v_lshlrev_b64 v[162:163], 10, v[186:187]
	v_lshl_add_u64 v[164:165], v[162:163], 0, v[184:185]
	v_or_b32_e32 v182, 0x80, v184
	v_ashrrev_i32_e32 v183, 31, v182
	s_waitcnt vmcnt(0)
	v_pk_add_f32 v[122:123], v[122:123], v[202:203]
	v_pk_add_f32 v[128:129], v[128:129], v[208:209]
	v_pk_add_f32 v[126:127], v[126:127], v[206:207]
	v_lshl_add_u64 v[206:207], v[164:165], 2, s[30:31]
	v_pk_add_f32 v[124:125], v[124:125], v[204:205]
	global_store_dwordx4 v[206:207], v[126:129], off nt
	global_store_dwordx4 v[206:207], v[122:125], off offset:16 nt
	v_cvt_pk_bf16_f32 v202, v126, v127
	v_cvt_pk_bf16_f32 v204, v122, v123
	v_mul_f32_e32 v127, v127, v127
	v_mul_f32_e32 v123, v123, v123
	v_fmac_f32_e32 v127, v126, v126
	v_mul_f32_e32 v126, v129, v129
	v_fmac_f32_e32 v123, v122, v122
	v_mul_f32_e32 v122, v125, v125
	v_fmac_f32_e32 v126, v128, v128
	v_fmac_f32_e32 v122, v124, v124
	v_cvt_pk_bf16_f32 v203, v128, v129
	v_cvt_pk_bf16_f32 v205, v124, v125
	v_lshl_add_u64 v[164:165], v[164:165], 1, s[28:29]
	v_add_f32_e32 v126, v127, v126
	v_add_f32_e32 v122, v123, v122
	v_pk_add_f32 v[120:121], v[120:121], v[216:217]
	v_pk_add_f32 v[118:119], v[118:119], v[214:215]
	v_pk_add_f32 v[114:115], v[114:115], v[146:147]
	global_store_dwordx4 v[164:165], v[202:205], off
	v_add_f32_e32 v128, v126, v122
	v_pk_add_f32 v[116:117], v[116:117], v[148:149]
	global_store_dwordx4 v[206:207], v[118:121], off offset:512 nt
	global_store_dwordx4 v[206:207], v[114:117], off offset:528 nt
	v_cvt_pk_bf16_f32 v122, v118, v119
	v_cvt_pk_bf16_f32 v124, v114, v115
	v_mul_f32_e32 v119, v119, v119
	v_mul_f32_e32 v115, v115, v115
	v_fmac_f32_e32 v119, v118, v118
	v_mul_f32_e32 v118, v121, v121
	v_fmac_f32_e32 v115, v114, v114
	v_mul_f32_e32 v114, v117, v117
	v_fmac_f32_e32 v118, v120, v120
	v_fmac_f32_e32 v114, v116, v116
	v_add_f32_e32 v118, v119, v118
	v_add_f32_e32 v114, v115, v114
	v_add_f32_e32 v114, v118, v114
	v_add_f32_e32 v114, v128, v114
	ds_bpermute_b32 v115, v200, v114
	v_lshl_add_u64 v[126:127], v[162:163], 0, v[182:183]
	v_cvt_pk_bf16_f32 v123, v120, v121
	v_cvt_pk_bf16_f32 v125, v116, v117
	v_lshl_add_u64 v[126:127], v[126:127], 1, s[28:29]
	s_waitcnt lgkmcnt(0)
	v_add_f32_e32 v114, v114, v115
	ds_bpermute_b32 v115, v199, v114
	global_store_dwordx4 v[126:127], v[122:125], off
	s_and_saveexec_b64 s[46:47], s[2:3]
	s_cbranch_execz .LBB0_971
	s_waitcnt lgkmcnt(0)
	v_add_f32_e32 v114, v114, v115
	ds_write_b32 v194, v114

; #define LAS __attribute__((address_space(3)))
;     DEVI f32x4 load(int r, int c) const { const bf16x4 y = *(const bf16x4*)(Y + (size_t)r * DM + c); return (f32x4){bf2f((u16)y[0]), bf2f((u16)y[1]), bf2f((u16)y[2]), bf2f((u16)y[3])}; }
; template <class Epi>
; DEVI void gemm_phase(LAS unsigned char* lds, const Gemm g, const Epi& E) {
;     ...
;             for (int am = 0; am < 4; ++am) {
;                 const int ai = am >> 1, m0 = (am & 1) * 2;
;                 f32x4 pre[2][2][2];
;                 if constexpr (Epi::PRE) {
; #pragma unroll
;                     for (int m = 0; m < 2; ++m)
; #pragma unroll
;                         for (int bj = 0; bj < 2; ++bj)
; #pragma unroll
;                             for (int n = 0; n < 2; ++n) pre[m][bj][n] = E.load(row0 + ai * HALF + (m0 + m) * 16, col0 + bj * HALF + n * NST);
;                 }
; #pragma unroll
;                 for (int mm = 0; mm < 2; ++mm) {
;                     const int m = m0 + mm;
;                     const int r = row0 + ai * HALF + m * 16; float rs = 1.f, part = 0.f;
;                     if constexpr (Epi::RS) rs = rsv[ai * 4 + m];
;                     if constexpr (Epi::PAIR) E.pair8(cur.b, r, cur.pn * HALF + wc * 32 + 8 * fq, acc[ai][0][m][0] * rs, acc[ai][0][m][1] * rs, acc[ai][1][m][0] * rs, acc[ai][1][m][1] * rs);
;                     else
; #pragma unroll
;                     for (int bj = 0; bj < 2; ++bj) {
;                         const int c = col0 + bj * HALF; f32x4 v0 = acc[ai][bj][m][0], v1 = acc[ai][bj][m][1];
;                         if constexpr (Epi::RS) { v0 = v0 * rs; v1 = v1 * rs; }
;                         if constexpr (Epi::PRE) part += E.frag_pre8(cur.b, r, c, v0, v1, pre[mm][bj][0], pre[mm][bj][1]);
;                         else if constexpr (Epi::PERM) E.frag8(cur.b, r, c, v0, v1);
;                         else { E.frag(cur.b, r, c, v0); E.frag(cur.b, r, c + 16, v1); }
;                     }
;                     if constexpr (Epi::SSQ) { part += __shfl_xor(part, 16); part += __shfl_xor(part, 32); if (fq == 0) ((LAS float*)(lds + 131072))[(wr * 4 + wc) * 128 + ai * 64 + m * 16 + fr] = part; }
.LBB0_973:
	s_or_b64 exec, exec, s[46:47]
	v_or_b32_e32 v132, 32, v186
	v_ashrrev_i32_e32 v133, 31, v132
	s_waitcnt lgkmcnt(0)
	v_lshlrev_b64 v[98:99], 12, v[132:133]
	v_lshl_add_u64 v[98:99], s[78:79], 0, v[98:99]
	v_lshl_add_u64 v[98:99], v[98:99], 0, v[188:189]
	global_load_dwordx4 v[116:119], v[98:99], off offset:16 nt
	global_load_dwordx4 v[120:123], v[98:99], off nt
	global_load_dwordx4 v[124:127], v[98:99], off offset:528 nt
	global_load_dwordx4 v[128:131], v[98:99], off offset:512 nt
	v_or_b32_e32 v114, 48, v186
	v_ashrrev_i32_e32 v115, 31, v114
	v_lshlrev_b64 v[98:99], 12, v[114:115]
	v_lshl_add_u64 v[98:99], s[78:79], 0, v[98:99]
	v_lshl_add_u64 v[102:103], v[98:99], 0, v[188:189]
	global_load_dwordx4 v[106:109], v[102:103], off offset:16 nt
	global_load_dwordx4 v[110:113], v[102:103], off nt
	global_load_dwordx4 v[98:101], v[102:103], off offset:528 nt
	s_nop 0
	global_load_dwordx4 v[102:105], v[102:103], off offset:512 nt
	v_lshlrev_b64 v[132:133], 10, v[132:133]
	v_lshl_add_u64 v[134:135], v[132:133], 0, v[184:185]
	s_waitcnt vmcnt(7)
	v_pk_add_f32 v[90:91], v[90:91], v[116:117]
	s_waitcnt vmcnt(6)
	v_pk_add_f32 v[96:97], v[96:97], v[122:123]
	v_pk_add_f32 v[94:95], v[94:95], v[120:121]
	v_lshl_add_u64 v[120:121], v[134:135], 2, s[30:31]
	v_pk_add_f32 v[92:93], v[92:93], v[118:119]
	global_store_dwordx4 v[120:121], v[94:97], off nt
	global_store_dwordx4 v[120:121], v[90:93], off offset:16 nt
	v_cvt_pk_bf16_f32 v116, v94, v95
	v_cvt_pk_bf16_f32 v118, v90, v91
	v_mul_f32_e32 v95, v95, v95
	v_mul_f32_e32 v91, v91, v91
	v_fmac_f32_e32 v95, v94, v94
	v_mul_f32_e32 v94, v97, v97
	v_fmac_f32_e32 v91, v90, v90
	v_mul_f32_e32 v90, v93, v93
	v_fmac_f32_e32 v94, v96, v96
	v_fmac_f32_e32 v90, v92, v92
	v_cvt_pk_bf16_f32 v117, v96, v97
	v_cvt_pk_bf16_f32 v119, v92, v93
	v_lshl_add_u64 v[122:123], v[134:135], 1, s[28:29]
	v_add_f32_e32 v94, v95, v94
	v_add_f32_e32 v90, v91, v90
	s_waitcnt vmcnt(6)
	v_pk_add_f32 v[88:89], v[88:89], v[130:131]
	v_pk_add_f32 v[86:87], v[86:87], v[128:129]
	v_pk_add_f32 v[82:83], v[82:83], v[124:125]
	global_store_dwordx4 v[122:123], v[116:119], off
	v_add_f32_e32 v96, v94, v90
	v_pk_add_f32 v[84:85], v[84:85], v[126:127]
	global_store_dwordx4 v[120:121], v[86:89], off offset:512 nt
	global_store_dwordx4 v[120:121], v[82:85], off offset:528 nt
	v_cvt_pk_bf16_f32 v90, v86, v87
	v_cvt_pk_bf16_f32 v92, v82, v83
	v_mul_f32_e32 v87, v87, v87
	v_mul_f32_e32 v83, v83, v83
	v_fmac_f32_e32 v87, v86, v86
	v_mul_f32_e32 v86, v89, v89
	v_fmac_f32_e32 v83, v82, v82
	v_mul_f32_e32 v82, v85, v85
	v_fmac_f32_e32 v86, v88, v88
	v_fmac_f32_e32 v82, v84, v84
	v_add_f32_e32 v86, v87, v86
	v_add_f32_e32 v82, v83, v82
	v_add_f32_e32 v82, v86, v82
	v_add_f32_e32 v82, v96, v82
	ds_bpermute_b32 v83, v200, v82
	v_lshl_add_u64 v[94:95], v[132:133], 0, v[182:183]
	v_cvt_pk_bf16_f32 v91, v88, v89
	v_cvt_pk_bf16_f32 v93, v84, v85
	v_lshl_add_u64 v[94:95], v[94:95], 1, s[28:29]
	s_waitcnt lgkmcnt(0)
	v_add_f32_e32 v82, v82, v83
	ds_bpermute_b32 v83, v199, v82
	global_store_dwordx4 v[94:95], v[90:93], off
	s_and_saveexec_b64 s[46:47], s[2:3]
	s_cbranch_execz .LBB0_975
	s_waitcnt lgkmcnt(0)
	v_add_f32_e32 v82, v82, v83
	ds_write_b32 v194, v82 offset:128

; #define LAS __attribute__((address_space(3)))
;     DEVI f32x4 load(int r, int c) const { const bf16x4 y = *(const bf16x4*)(Y + (size_t)r * DM + c); return (f32x4){bf2f((u16)y[0]), bf2f((u16)y[1]), bf2f((u16)y[2]), bf2f((u16)y[3])}; }
; template <class Epi>
; DEVI void gemm_phase(LAS unsigned char* lds, const Gemm g, const Epi& E) {
;     ...
;             for (int am = 0; am < 4; ++am) {
;                 const int ai = am >> 1, m0 = (am & 1) * 2;
;                 f32x4 pre[2][2][2];
;                 if constexpr (Epi::PRE) {
; #pragma unroll
;                     for (int m = 0; m < 2; ++m)
; #pragma unroll
;                         for (int bj = 0; bj < 2; ++bj)
; #pragma unroll
;                             for (int n = 0; n < 2; ++n) pre[m][bj][n] = E.load(row0 + ai * HALF + (m0 + m) * 16, col0 + bj * HALF + n * NST);
;                 }
; #pragma unroll
;                 for (int mm = 0; mm < 2; ++mm) {
;                     const int m = m0 + mm;
;                     const int r = row0 + ai * HALF + m * 16; float rs = 1.f, part = 0.f;
;                     if constexpr (Epi::RS) rs = rsv[ai * 4 + m];
;                     if constexpr (Epi::PAIR) E.pair8(cur.b, r, cur.pn * HALF + wc * 32 + 8 * fq, acc[ai][0][m][0] * rs, acc[ai][0][m][1] * rs, acc[ai][1][m][0] * rs, acc[ai][1][m][1] * rs);
;                     else
; #pragma unroll
;                     for (int bj = 0; bj < 2; ++bj) {
;                         const int c = col0 + bj * HALF; f32x4 v0 = acc[ai][bj][m][0], v1 = acc[ai][bj][m][1];
;                         if constexpr (Epi::RS) { v0 = v0 * rs; v1 = v1 * rs; }
;                         if constexpr (Epi::PRE) part += E.frag_pre8(cur.b, r, c, v0, v1, pre[mm][bj][0], pre[mm][bj][1]);
;                         else if constexpr (Epi::PERM) E.frag8(cur.b, r, c, v0, v1);
;                         else { E.frag(cur.b, r, c, v0); E.frag(cur.b, r, c + 16, v1); }
;                     }
;                     if constexpr (Epi::SSQ) { part += __shfl_xor(part, 16); part += __shfl_xor(part, 32); if (fq == 0) ((LAS float*)(lds + 131072))[(wr * 4 + wc) * 128 + ai * 64 + m * 16 + fr] = part; }
.LBB0_977:
	s_or_b64 exec, exec, s[46:47]
	v_add_u32_e32 v100, 0x80, v186
	v_ashrrev_i32_e32 v101, 31, v100
	s_waitcnt lgkmcnt(0)
	v_lshlrev_b64 v[66:67], 12, v[100:101]
	v_lshl_add_u64 v[66:67], s[78:79], 0, v[66:67]
	v_lshl_add_u64 v[66:67], v[66:67], 0, v[188:189]
	global_load_dwordx4 v[84:87], v[66:67], off offset:16 nt
	global_load_dwordx4 v[88:91], v[66:67], off nt
	global_load_dwordx4 v[92:95], v[66:67], off offset:528 nt
	global_load_dwordx4 v[96:99], v[66:67], off offset:512 nt
	v_add_u32_e32 v82, 0x90, v186
	v_ashrrev_i32_e32 v83, 31, v82
	v_lshlrev_b64 v[66:67], 12, v[82:83]
	v_lshl_add_u64 v[66:67], s[78:79], 0, v[66:67]
	v_lshl_add_u64 v[70:71], v[66:67], 0, v[188:189]
	global_load_dwordx4 v[74:77], v[70:71], off offset:16 nt
	global_load_dwordx4 v[78:81], v[70:71], off nt
	global_load_dwordx4 v[66:69], v[70:71], off offset:528 nt
	s_nop 0
	global_load_dwordx4 v[70:73], v[70:71], off offset:512 nt
	v_lshlrev_b64 v[100:101], 10, v[100:101]
	v_lshl_add_u64 v[102:103], v[100:101], 0, v[184:185]
	s_waitcnt vmcnt(7)
	v_pk_add_f32 v[58:59], v[58:59], v[84:85]
	s_waitcnt vmcnt(6)
	v_pk_add_f32 v[64:65], v[64:65], v[90:91]
	v_pk_add_f32 v[62:63], v[62:63], v[88:89]
	v_lshl_add_u64 v[88:89], v[102:103], 2, s[30:31]
	v_pk_add_f32 v[60:61], v[60:61], v[86:87]
	global_store_dwordx4 v[88:89], v[62:65], off nt
	global_store_dwordx4 v[88:89], v[58:61], off offset:16 nt
	v_cvt_pk_bf16_f32 v84, v62, v63
	v_cvt_pk_bf16_f32 v86, v58, v59
	v_mul_f32_e32 v63, v63, v63
	v_mul_f32_e32 v59, v59, v59
	v_fmac_f32_e32 v63, v62, v62
	v_mul_f32_e32 v62, v65, v65
	v_fmac_f32_e32 v59, v58, v58
	v_mul_f32_e32 v58, v61, v61
	v_fmac_f32_e32 v62, v64, v64
	v_fmac_f32_e32 v58, v60, v60
	v_cvt_pk_bf16_f32 v85, v64, v65
	v_cvt_pk_bf16_f32 v87, v60, v61
	v_lshl_add_u64 v[90:91], v[102:103], 1, s[28:29]
	v_add_f32_e32 v62, v63, v62
	v_add_f32_e32 v58, v59, v58
	s_waitcnt vmcnt(6)
	v_pk_add_f32 v[56:57], v[56:57], v[98:99]
	v_pk_add_f32 v[54:55], v[54:55], v[96:97]
	v_pk_add_f32 v[50:51], v[50:51], v[92:93]
	global_store_dwordx4 v[90:91], v[84:87], off
	v_add_f32_e32 v64, v62, v58
	v_pk_add_f32 v[52:53], v[52:53], v[94:95]
	global_store_dwordx4 v[88:89], v[54:57], off offset:512 nt
	global_store_dwordx4 v[88:89], v[50:53], off offset:528 nt
	v_cvt_pk_bf16_f32 v58, v54, v55
	v_cvt_pk_bf16_f32 v60, v50, v51
	v_mul_f32_e32 v55, v55, v55
	v_mul_f32_e32 v51, v51, v51
	v_fmac_f32_e32 v55, v54, v54
	v_mul_f32_e32 v54, v57, v57
	v_fmac_f32_e32 v51, v50, v50
	v_mul_f32_e32 v50, v53, v53
	v_fmac_f32_e32 v54, v56, v56
	v_fmac_f32_e32 v50, v52, v52
	v_add_f32_e32 v54, v55, v54
	v_add_f32_e32 v50, v51, v50
	v_add_f32_e32 v50, v54, v50
	v_add_f32_e32 v50, v64, v50
	ds_bpermute_b32 v51, v200, v50
	v_lshl_add_u64 v[62:63], v[100:101], 0, v[182:183]
	v_cvt_pk_bf16_f32 v59, v56, v57
	v_cvt_pk_bf16_f32 v61, v52, v53
	v_lshl_add_u64 v[62:63], v[62:63], 1, s[28:29]
	s_waitcnt lgkmcnt(0)
	v_add_f32_e32 v50, v50, v51
	ds_bpermute_b32 v51, v199, v50
	global_store_dwordx4 v[62:63], v[58:61], off
	s_and_saveexec_b64 s[46:47], s[2:3]
	s_cbranch_execz .LBB0_979
	s_waitcnt lgkmcnt(0)
	v_add_f32_e32 v50, v50, v51
	ds_write_b32 v194, v50 offset:256

; #define LAS __attribute__((address_space(3)))
;     DEVI f32x4 load(int r, int c) const { const bf16x4 y = *(const bf16x4*)(Y + (size_t)r * DM + c); return (f32x4){bf2f((u16)y[0]), bf2f((u16)y[1]), bf2f((u16)y[2]), bf2f((u16)y[3])}; }
; template <class Epi>
; DEVI void gemm_phase(LAS unsigned char* lds, const Gemm g, const Epi& E) {
;     ...
;             for (int am = 0; am < 4; ++am) {
;                 const int ai = am >> 1, m0 = (am & 1) * 2;
;                 f32x4 pre[2][2][2];
;                 if constexpr (Epi::PRE) {
; #pragma unroll
;                     for (int m = 0; m < 2; ++m)
; #pragma unroll
;                         for (int bj = 0; bj < 2; ++bj)
; #pragma unroll
;                             for (int n = 0; n < 2; ++n) pre[m][bj][n] = E.load(row0 + ai * HALF + (m0 + m) * 16, col0 + bj * HALF + n * NST);
;                 }
; #pragma unroll
;                 for (int mm = 0; mm < 2; ++mm) {
;                     const int m = m0 + mm;
;                     const int r = row0 + ai * HALF + m * 16; float rs = 1.f, part = 0.f;
;                     if constexpr (Epi::RS) rs = rsv[ai * 4 + m];
;                     if constexpr (Epi::PAIR) E.pair8(cur.b, r, cur.pn * HALF + wc * 32 + 8 * fq, acc[ai][0][m][0] * rs, acc[ai][0][m][1] * rs, acc[ai][1][m][0] * rs, acc[ai][1][m][1] * rs);
;                     else
; #pragma unroll
;                     for (int bj = 0; bj < 2; ++bj) {
;                         const int c = col0 + bj * HALF; f32x4 v0 = acc[ai][bj][m][0], v1 = acc[ai][bj][m][1];
;                         if constexpr (Epi::RS) { v0 = v0 * rs; v1 = v1 * rs; }
;                         if constexpr (Epi::PRE) part += E.frag_pre8(cur.b, r, c, v0, v1, pre[mm][bj][0], pre[mm][bj][1]);
;                         else if constexpr (Epi::PERM) E.frag8(cur.b, r, c, v0, v1);
;                         else { E.frag(cur.b, r, c, v0); E.frag(cur.b, r, c + 16, v1); }
;                     }
;                     if constexpr (Epi::SSQ) { part += __shfl_xor(part, 16); part += __shfl_xor(part, 32); if (fq == 0) ((LAS float*)(lds + 131072))[(wr * 4 + wc) * 128 + ai * 64 + m * 16 + fr] = part; }
.LBB0_981:
	s_or_b64 exec, exec, s[46:47]
	v_add_u32_e32 v68, 0xa0, v186
	v_ashrrev_i32_e32 v69, 31, v68
	s_waitcnt lgkmcnt(0)
	v_lshlrev_b64 v[34:35], 12, v[68:69]
	v_lshl_add_u64 v[34:35], s[78:79], 0, v[34:35]
	v_lshl_add_u64 v[34:35], v[34:35], 0, v[188:189]
	global_load_dwordx4 v[52:55], v[34:35], off offset:16 nt
	global_load_dwordx4 v[56:59], v[34:35], off nt
	global_load_dwordx4 v[60:63], v[34:35], off offset:528 nt
	global_load_dwordx4 v[64:67], v[34:35], off offset:512 nt
	v_add_u32_e32 v50, 0xb0, v186
	v_ashrrev_i32_e32 v51, 31, v50
	v_lshlrev_b64 v[34:35], 12, v[50:51]
	v_lshl_add_u64 v[34:35], s[78:79], 0, v[34:35]
	v_lshl_add_u64 v[38:39], v[34:35], 0, v[188:189]
	global_load_dwordx4 v[42:45], v[38:39], off offset:16 nt
	global_load_dwordx4 v[46:49], v[38:39], off nt
	global_load_dwordx4 v[34:37], v[38:39], off offset:528 nt
	s_nop 0
	global_load_dwordx4 v[38:41], v[38:39], off offset:512 nt
	v_lshlrev_b64 v[68:69], 10, v[68:69]
	v_lshl_add_u64 v[70:71], v[68:69], 0, v[184:185]
	s_waitcnt vmcnt(7)
	v_pk_add_f32 v[26:27], v[26:27], v[52:53]
	s_waitcnt vmcnt(6)
	v_pk_add_f32 v[32:33], v[32:33], v[58:59]
	v_pk_add_f32 v[30:31], v[30:31], v[56:57]
	v_lshl_add_u64 v[56:57], v[70:71], 2, s[30:31]
	v_pk_add_f32 v[28:29], v[28:29], v[54:55]
	global_store_dwordx4 v[56:57], v[30:33], off nt
	global_store_dwordx4 v[56:57], v[26:29], off offset:16 nt
	v_cvt_pk_bf16_f32 v52, v30, v31
	v_cvt_pk_bf16_f32 v54, v26, v27
	v_mul_f32_e32 v31, v31, v31
	v_mul_f32_e32 v27, v27, v27
	v_fmac_f32_e32 v31, v30, v30
	v_mul_f32_e32 v30, v33, v33
	v_fmac_f32_e32 v27, v26, v26
	v_mul_f32_e32 v26, v29, v29
	v_fmac_f32_e32 v30, v32, v32
	v_fmac_f32_e32 v26, v28, v28
	v_cvt_pk_bf16_f32 v53, v32, v33
	v_cvt_pk_bf16_f32 v55, v28, v29
	v_lshl_add_u64 v[58:59], v[70:71], 1, s[28:29]
	v_add_f32_e32 v30, v31, v30
	v_add_f32_e32 v26, v27, v26
	s_waitcnt vmcnt(6)
	v_pk_add_f32 v[24:25], v[24:25], v[66:67]
	v_pk_add_f32 v[22:23], v[22:23], v[64:65]
	v_pk_add_f32 v[18:19], v[18:19], v[60:61]
	global_store_dwordx4 v[58:59], v[52:55], off
	v_add_f32_e32 v32, v30, v26
	v_pk_add_f32 v[20:21], v[20:21], v[62:63]
	global_store_dwordx4 v[56:57], v[22:25], off offset:512 nt
	global_store_dwordx4 v[56:57], v[18:21], off offset:528 nt
	v_cvt_pk_bf16_f32 v26, v22, v23
	v_cvt_pk_bf16_f32 v28, v18, v19
	v_mul_f32_e32 v23, v23, v23
	v_mul_f32_e32 v19, v19, v19
	v_fmac_f32_e32 v23, v22, v22
	v_mul_f32_e32 v22, v25, v25
	v_fmac_f32_e32 v19, v18, v18
	v_mul_f32_e32 v18, v21, v21
	v_fmac_f32_e32 v22, v24, v24
	v_fmac_f32_e32 v18, v20, v20
	v_add_f32_e32 v22, v23, v22
	v_add_f32_e32 v18, v19, v18
	v_add_f32_e32 v18, v22, v18
	v_add_f32_e32 v18, v32, v18
	ds_bpermute_b32 v19, v200, v18
	v_lshl_add_u64 v[30:31], v[68:69], 0, v[182:183]
	v_cvt_pk_bf16_f32 v27, v24, v25
	v_cvt_pk_bf16_f32 v29, v20, v21
	v_lshl_add_u64 v[30:31], v[30:31], 1, s[28:29]
	s_waitcnt lgkmcnt(0)
	v_add_f32_e32 v18, v18, v19
	ds_bpermute_b32 v19, v199, v18
	global_store_dwordx4 v[30:31], v[26:29], off
	s_and_saveexec_b64 s[46:47], s[2:3]
	s_cbranch_execz .LBB0_983
	s_waitcnt lgkmcnt(0)
	v_add_f32_e32 v18, v18, v19
	ds_write_b32 v194, v18 offset:384

; #define PG8_STAGE(bufoff, gbase, voff) do { _Pragma("unroll") for (int _i = 0; _i < 2; ++_i) \
;         __builtin_amdgcn_global_load_lds((const unsigned*)((const char*)(gbase) + (voff)[_i]), (LAS unsigned*)(lds + (bufoff) + ldsw + _i * 8192), 16, 0, 0); } while (0)
; #define PG8_LDA(dst, b, h) do { _Pragma("unroll") for (int m = 0; m < 4; ++m) _Pragma("unroll") for (int k = 0; k < 2; ++k) dst[m][k] = *(const LAS bf16x8*)(lds + PG8_SA(b, h) + aoff + m * 2048 + k * 1024); } while (0)
; #define PG8_LDB(dst, b, h) do { _Pragma("unroll") for (int n = 0; n < 2; ++n) _Pragma("unroll") for (int k = 0; k < 2; ++k) dst[n][k] = *(const LAS bf16x8*)(lds + PG8_SB(b, h) + boff + n * 2048 + k * 1024); } while (0)
; #define PG8_MMA(ai, bj, At, Bt) do { __builtin_amdgcn_s_setprio(1); _Pragma("unroll") for (int m = 0; m < 4; ++m) _Pragma("unroll") for (int n = 0; n < 2; ++n) _Pragma("unroll") for (int k = 0; k < 2; ++k) \
;         acc[ai][bj][m][n] = __builtin_amdgcn_mfma_f32_16x16x32_bf16(Bt[n][k], At[m][k], acc[ai][bj][m][n], 0, 0, 0); __builtin_amdgcn_s_setprio(0); } while (0)
; #define PG8_WAIT_L(n) asm volatile("s_waitcnt lgkmcnt(" #n ")" ::: "memory")
; #define PG8_BAR __builtin_amdgcn_s_barrier()
; #define PG8_SCHED __builtin_amdgcn_sched_barrier(0)
; template <class Epi>
; DEVI void gemm_phase(LAS unsigned char* lds, const Gemm g, const Epi& E) {
;     ...
;         for (int t = 0; t < nt; t += 2) {
;             const bool last = (t == nt - 2);
;             const char* a1 = cA + (size_t)(t + 1) * kstep;
;             const char* a2 = last ? nA : cA + (size_t)(t + 2) * kstep; const char* b2 = last ? nB : cB + (size_t)(t + 2) * kstep;
;             const char* a3 = a2 + kstep; const char* b3 = b2 + kstep;
;             PG8_LDB(B0, 0, 0); PG8_SCHED; PG8_LDA(At, 0, 0); PG8_STAGE(PG8_SA(1, 1), a1 + hstepA, voffA);
;             PG8_WAIT_L(8); PG8_BAR; PG8_WAIT_L(0); PG8_MMA(0, 0, At, B0); PG8_BAR; PG8_SCHED;
;             PG8_LDB(B1, 0, 1); PG8_STAGE(PG8_SB(0, 0), b2, voffB);
;             PG8_BAR; PG8_WAIT_L(0); PG8_MMA(0, 1, At, B1); PG8_BAR;
;             PG8_LDA(At, 0, 1); PG8_STAGE(PG8_SA(0, 0), a2, voffA);
;             PG8_BAR; PG8_WAIT_L(0); PG8_MMA(1, 0, At, B0); PG8_BAR; PG8_SCHED;
.LBB0_1595:
	s_add_u32 s18, s8, 0xfffc0080
	s_addc_u32 s19, s9, -1
	s_add_i32 s26, 0, 0x10000
	v_add_u32_e32 v142, s26, v191
	ds_read_b128 v[130:133], v142
	ds_read_b128 v[134:137], v142 offset:1024
	ds_read_b128 v[138:141], v142 offset:2048
	ds_read_b128 v[142:145], v142 offset:3072
	s_cmp_eq_u32 s17, 12
	s_cselect_b32 s81, s0, s19
	s_cselect_b32 s80, s1, s18
	s_cselect_b32 s79, s37, s15
	s_cselect_b32 s78, s36, s13
	v_lshl_add_u64 v[162:163], s[8:9], 0, v[152:153]
	s_add_i32 m0, s69, 0xc000
	ds_read_b128 v[178:181], v196
	ds_read_b128 v[182:185], v196 offset:1024
	ds_read_b128 v[186:189], v196 offset:2048
	ds_read_b128 v[198:201], v196 offset:3072
	ds_read_b128 v[202:205], v196 offset:4096
	ds_read_b128 v[206:209], v196 offset:5120
	ds_read_b128 v[214:217], v196 offset:6144
	ds_read_b128 v[218:221], v196 offset:7168
	global_load_lds_dwordx4 v[162:163], off
	s_add_i32 m0, s69, 0xe000
	v_lshl_add_u64 v[162:163], s[8:9], 0, v[176:177]
	global_load_lds_dwordx4 v[162:163], off
	s_waitcnt lgkmcnt(8)
	s_barrier
	s_waitcnt lgkmcnt(0)
	v_mfma_f32_16x16x32_bf16 v[126:129], v[130:133], v[178:181], v[126:129]
	v_mfma_f32_16x16x32_bf16 v[122:125], v[138:141], v[178:181], v[122:125]
	v_mfma_f32_16x16x32_bf16 v[110:113], v[130:133], v[186:189], v[110:113]
	v_mfma_f32_16x16x32_bf16 v[106:109], v[138:141], v[186:189], v[106:109]
	v_mfma_f32_16x16x32_bf16 v[94:97], v[130:133], v[202:205], v[94:97]
	v_mfma_f32_16x16x32_bf16 v[90:93], v[138:141], v[202:205], v[90:93]
	v_mfma_f32_16x16x32_bf16 v[78:81], v[130:133], v[214:217], v[78:81]
	v_mfma_f32_16x16x32_bf16 v[74:77], v[138:141], v[214:217], v[74:77]
	v_mfma_f32_16x16x32_bf16 v[126:129], v[134:137], v[182:185], v[126:129]
	v_mfma_f32_16x16x32_bf16 v[122:125], v[142:145], v[182:185], v[122:125]
	v_mfma_f32_16x16x32_bf16 v[110:113], v[134:137], v[198:201], v[110:113]
	v_mfma_f32_16x16x32_bf16 v[106:109], v[142:145], v[198:201], v[106:109]
	v_mfma_f32_16x16x32_bf16 v[94:97], v[134:137], v[206:209], v[94:97]
	v_mfma_f32_16x16x32_bf16 v[90:93], v[142:145], v[206:209], v[90:93]
	v_mfma_f32_16x16x32_bf16 v[78:81], v[134:137], v[218:221], v[78:81]
	v_mfma_f32_16x16x32_bf16 v[74:77], v[142:145], v[218:221], v[74:77]
	s_barrier
	s_add_i32 s27, 0, 0x14000
	v_add_u32_e32 v162, s27, v191
	s_add_i32 s18, s26, s82
	ds_read_b128 v[222:225], v162
	ds_read_b128 v[226:229], v162 offset:1024
	ds_read_b128 v[230:233], v162 offset:2048
	ds_read_b128 v[234:237], v162 offset:3072
	v_lshl_add_u64 v[162:163], s[78:79], 0, v[8:9]
	s_mov_b32 m0, s18
	v_lshl_add_u64 v[164:165], s[78:79], 0, v[150:151]
	global_load_lds_dwordx4 v[162:163], off
	s_add_i32 m0, s18, 0x2000
	s_nop 0
	global_load_lds_dwordx4 v[164:165], off
	s_barrier
	s_waitcnt lgkmcnt(0)
	v_mfma_f32_16x16x32_bf16 v[118:121], v[222:225], v[178:181], v[118:121]
	v_mfma_f32_16x16x32_bf16 v[114:117], v[230:233], v[178:181], v[114:117]
	v_mfma_f32_16x16x32_bf16 v[102:105], v[222:225], v[186:189], v[102:105]
	v_mfma_f32_16x16x32_bf16 v[98:101], v[230:233], v[186:189], v[98:101]
	v_mfma_f32_16x16x32_bf16 v[86:89], v[222:225], v[202:205], v[86:89]
	v_mfma_f32_16x16x32_bf16 v[82:85], v[230:233], v[202:205], v[82:85]
	v_mfma_f32_16x16x32_bf16 v[70:73], v[222:225], v[214:217], v[70:73]
	v_mfma_f32_16x16x32_bf16 v[66:69], v[230:233], v[214:217], v[66:69]
	v_mfma_f32_16x16x32_bf16 v[118:121], v[226:229], v[182:185], v[118:121]
	v_mfma_f32_16x16x32_bf16 v[114:117], v[234:237], v[182:185], v[114:117]
	v_mfma_f32_16x16x32_bf16 v[102:105], v[226:229], v[198:201], v[102:105]
	v_mfma_f32_16x16x32_bf16 v[98:101], v[234:237], v[198:201], v[98:101]
	v_mfma_f32_16x16x32_bf16 v[86:89], v[226:229], v[206:209], v[86:89]
	v_mfma_f32_16x16x32_bf16 v[82:85], v[234:237], v[206:209], v[82:85]
	v_mfma_f32_16x16x32_bf16 v[70:73], v[226:229], v[218:221], v[70:73]
	v_mfma_f32_16x16x32_bf16 v[66:69], v[234:237], v[218:221], v[66:69]
	s_mov_b32 m0, s69
	v_lshl_add_u64 v[238:239], s[80:81], 0, v[146:147]
	s_barrier
	ds_read_b128 v[178:181], v196 offset:16384
	ds_read_b128 v[182:185], v196 offset:17408
	ds_read_b128 v[186:189], v196 offset:18432
	ds_read_b128 v[198:201], v196 offset:19456
	ds_read_b128 v[202:205], v196 offset:20480
	ds_read_b128 v[206:209], v196 offset:21504
	ds_read_b128 v[214:217], v196 offset:22528
	ds_read_b128 v[218:221], v196 offset:23552
	global_load_lds_dwordx4 v[238:239], off
	s_mov_b32 m0, s83
	v_lshl_add_u64 v[240:241], s[80:81], 0, v[148:149]
	global_load_lds_dwordx4 v[240:241], off
	s_barrier
	s_waitcnt lgkmcnt(0)
	v_mfma_f32_16x16x32_bf16 v[62:65], v[130:133], v[178:181], v[62:65]
	v_mfma_f32_16x16x32_bf16 v[58:61], v[138:141], v[178:181], v[58:61]
	v_mfma_f32_16x16x32_bf16 v[46:49], v[130:133], v[186:189], v[46:49]
	v_mfma_f32_16x16x32_bf16 v[42:45], v[138:141], v[186:189], v[42:45]
	v_mfma_f32_16x16x32_bf16 v[30:33], v[130:133], v[202:205], v[30:33]
	v_mfma_f32_16x16x32_bf16 v[26:29], v[138:141], v[202:205], v[26:29]
	v_mfma_f32_16x16x32_bf16 v[14:17], v[130:133], v[214:217], v[14:17]
	v_mfma_f32_16x16x32_bf16 v[10:13], v[138:141], v[214:217], v[10:13]
	v_mfma_f32_16x16x32_bf16 v[62:65], v[134:137], v[182:185], v[62:65]
	v_mfma_f32_16x16x32_bf16 v[58:61], v[142:145], v[182:185], v[58:61]
	v_mfma_f32_16x16x32_bf16 v[46:49], v[134:137], v[198:201], v[46:49]
	v_mfma_f32_16x16x32_bf16 v[42:45], v[142:145], v[198:201], v[42:45]
	v_mfma_f32_16x16x32_bf16 v[30:33], v[134:137], v[206:209], v[30:33]
	v_mfma_f32_16x16x32_bf16 v[26:29], v[142:145], v[206:209], v[26:29]
	v_mfma_f32_16x16x32_bf16 v[14:17], v[134:137], v[218:221], v[14:17]
	v_mfma_f32_16x16x32_bf16 v[10:13], v[142:145], v[218:221], v[10:13]
	s_barrier
; #define PG8_STAGE(bufoff, gbase, voff) do { _Pragma("unroll") for (int _i = 0; _i < 2; ++_i) \
;         __builtin_amdgcn_global_load_lds((const unsigned*)((const char*)(gbase) + (voff)[_i]), (LAS unsigned*)(lds + (bufoff) + ldsw + _i * 8192), 16, 0, 0); } while (0)
; #define PG8_LDA(dst, b, h) do { _Pragma("unroll") for (int m = 0; m < 4; ++m) _Pragma("unroll") for (int k = 0; k < 2; ++k) dst[m][k] = *(const LAS bf16x8*)(lds + PG8_SA(b, h) + aoff + m * 2048 + k * 1024); } while (0)
; #define PG8_LDB(dst, b, h) do { _Pragma("unroll") for (int n = 0; n < 2; ++n) _Pragma("unroll") for (int k = 0; k < 2; ++k) dst[n][k] = *(const LAS bf16x8*)(lds + PG8_SB(b, h) + boff + n * 2048 + k * 1024); } while (0)
; #define PG8_MMA(ai, bj, At, Bt) do { __builtin_amdgcn_s_setprio(1); _Pragma("unroll") for (int m = 0; m < 4; ++m) _Pragma("unroll") for (int n = 0; n < 2; ++n) _Pragma("unroll") for (int k = 0; k < 2; ++k) \
;         acc[ai][bj][m][n] = __builtin_amdgcn_mfma_f32_16x16x32_bf16(Bt[n][k], At[m][k], acc[ai][bj][m][n], 0, 0, 0); __builtin_amdgcn_s_setprio(0); } while (0)
; #define PG8_WAIT_V(n) asm volatile("s_waitcnt vmcnt(" #n ")" ::: "memory")
; #define PG8_WAIT_L(n) asm volatile("s_waitcnt lgkmcnt(" #n ")" ::: "memory")
; #define PG8_BAR __builtin_amdgcn_s_barrier()
; #define PG8_SCHED __builtin_amdgcn_sched_barrier(0)
; template <class Epi>
; DEVI void gemm_phase(LAS unsigned char* lds, const Gemm g, const Epi& E) {
;     ...
;             PG8_STAGE(PG8_SB(0, 1), b2 + hstepB, voffB);
;             PG8_WAIT_V(6); PG8_BAR; PG8_MMA(1, 1, At, B1); PG8_BAR;
;             PG8_LDB(B0, 1, 0); PG8_SCHED; PG8_LDA(At, 1, 0); PG8_STAGE(PG8_SA(0, 1), a2 + hstepA, voffA);
;             PG8_WAIT_L(8); PG8_BAR; PG8_WAIT_L(0); PG8_MMA(0, 0, At, B0); PG8_BAR; PG8_SCHED;
;             PG8_LDB(B1, 1, 1); PG8_STAGE(PG8_SB(1, 0), b3, voffB);
;             PG8_BAR; PG8_WAIT_L(0); PG8_MMA(0, 1, At, B1); PG8_BAR;
;             PG8_LDA(At, 1, 1); PG8_STAGE(PG8_SA(1, 0), a3, voffA);
;             PG8_BAR; PG8_WAIT_L(0); PG8_MMA(1, 0, At, B0); PG8_BAR; PG8_SCHED;
;             PG8_STAGE(PG8_SB(1, 1), b3 + hstepB, voffB);
;             PG8_WAIT_V(6); PG8_BAR; PG8_MMA(1, 1, At, B1); PG8_BAR;
	s_add_u32 s18, s78, 0x40000
	s_addc_u32 s19, s79, 0
	s_add_i32 s26, s27, s82
	s_mov_b32 m0, s26
	v_lshl_add_u64 v[130:131], s[18:19], 0, v[8:9]
	global_load_lds_dwordx4 v[130:131], off
	s_add_i32 m0, s26, 0x2000
	v_lshl_add_u64 v[130:131], s[18:19], 0, v[150:151]
	global_load_lds_dwordx4 v[130:131], off
	s_waitcnt vmcnt(6)
	s_barrier
	v_mfma_f32_16x16x32_bf16 v[54:57], v[222:225], v[178:181], v[54:57]
	v_mfma_f32_16x16x32_bf16 v[50:53], v[230:233], v[178:181], v[50:53]
	v_mfma_f32_16x16x32_bf16 v[38:41], v[222:225], v[186:189], v[38:41]
	v_mfma_f32_16x16x32_bf16 v[34:37], v[230:233], v[186:189], v[34:37]
	v_mfma_f32_16x16x32_bf16 v[22:25], v[222:225], v[202:205], v[22:25]
	v_mfma_f32_16x16x32_bf16 v[18:21], v[230:233], v[202:205], v[18:21]
	v_mfma_f32_16x16x32_bf16 v[4:7], v[222:225], v[214:217], v[4:7]
	v_mfma_f32_16x16x32_bf16 v[0:3], v[230:233], v[214:217], v[0:3]
	v_mfma_f32_16x16x32_bf16 v[54:57], v[226:229], v[182:185], v[54:57]
	v_mfma_f32_16x16x32_bf16 v[50:53], v[234:237], v[182:185], v[50:53]
	v_mfma_f32_16x16x32_bf16 v[38:41], v[226:229], v[198:201], v[38:41]
	v_mfma_f32_16x16x32_bf16 v[34:37], v[234:237], v[198:201], v[34:37]
	v_mfma_f32_16x16x32_bf16 v[22:25], v[226:229], v[206:209], v[22:25]
	v_mfma_f32_16x16x32_bf16 v[18:21], v[234:237], v[206:209], v[18:21]
	v_mfma_f32_16x16x32_bf16 v[4:7], v[226:229], v[218:221], v[4:7]
	v_mfma_f32_16x16x32_bf16 v[0:3], v[234:237], v[218:221], v[0:3]
	s_add_i32 s26, 0, 0x18000
	v_add_u32_e32 v142, s26, v191
	s_barrier
	ds_read_b128 v[130:133], v142
	ds_read_b128 v[134:137], v142 offset:1024
	ds_read_b128 v[138:141], v142 offset:2048
	ds_read_b128 v[142:145], v142 offset:3072
	s_add_u32 s18, s80, 0x40000
	s_addc_u32 s19, s81, 0
	s_mov_b32 m0, s84
	v_lshl_add_u64 v[222:223], s[18:19], 0, v[146:147]
	ds_read_b128 v[178:181], v196 offset:32768
	ds_read_b128 v[182:185], v196 offset:33792
	ds_read_b128 v[186:189], v196 offset:34816
	ds_read_b128 v[198:201], v196 offset:35840
	ds_read_b128 v[202:205], v196 offset:36864
	ds_read_b128 v[206:209], v196 offset:37888
	ds_read_b128 v[214:217], v196 offset:38912
	ds_read_b128 v[218:221], v196 offset:39936
	global_load_lds_dwordx4 v[222:223], off
	s_mov_b32 m0, s85
	v_lshl_add_u64 v[222:223], s[18:19], 0, v[148:149]
	global_load_lds_dwordx4 v[222:223], off
	s_waitcnt lgkmcnt(8)
	s_barrier
	s_waitcnt lgkmcnt(0)
	v_mfma_f32_16x16x32_bf16 v[126:129], v[130:133], v[178:181], v[126:129]
	v_mfma_f32_16x16x32_bf16 v[122:125], v[138:141], v[178:181], v[122:125]
	v_mfma_f32_16x16x32_bf16 v[110:113], v[130:133], v[186:189], v[110:113]
	v_mfma_f32_16x16x32_bf16 v[106:109], v[138:141], v[186:189], v[106:109]
	v_mfma_f32_16x16x32_bf16 v[94:97], v[130:133], v[202:205], v[94:97]
	v_mfma_f32_16x16x32_bf16 v[90:93], v[138:141], v[202:205], v[90:93]
	v_mfma_f32_16x16x32_bf16 v[78:81], v[130:133], v[214:217], v[78:81]
	v_mfma_f32_16x16x32_bf16 v[74:77], v[138:141], v[214:217], v[74:77]
	v_mfma_f32_16x16x32_bf16 v[126:129], v[134:137], v[182:185], v[126:129]
	v_mfma_f32_16x16x32_bf16 v[122:125], v[142:145], v[182:185], v[122:125]
	v_mfma_f32_16x16x32_bf16 v[110:113], v[134:137], v[198:201], v[110:113]
	v_mfma_f32_16x16x32_bf16 v[106:109], v[142:145], v[198:201], v[106:109]
	v_mfma_f32_16x16x32_bf16 v[94:97], v[134:137], v[206:209], v[94:97]
	v_mfma_f32_16x16x32_bf16 v[90:93], v[142:145], v[206:209], v[90:93]
	v_mfma_f32_16x16x32_bf16 v[78:81], v[134:137], v[218:221], v[78:81]
	v_mfma_f32_16x16x32_bf16 v[74:77], v[142:145], v[218:221], v[74:77]
	s_barrier
	s_add_i32 s27, 0, 0x1c000
	s_add_i32 s18, s26, s82
	v_add_u32_e32 v197, s27, v191
	v_lshl_add_u64 v[162:163], v[162:163], 0, s[70:71]
	s_mov_b32 m0, s18
	ds_read_b128 v[222:225], v197
	ds_read_b128 v[226:229], v197 offset:1024
	ds_read_b128 v[230:233], v197 offset:2048
	ds_read_b128 v[234:237], v197 offset:3072
	global_load_lds_dwordx4 v[162:163], off
	s_add_i32 m0, s18, 0x2000
	v_lshl_add_u64 v[162:163], v[164:165], 0, s[70:71]
	global_load_lds_dwordx4 v[162:163], off
	s_barrier
	s_waitcnt lgkmcnt(0)
	v_mfma_f32_16x16x32_bf16 v[118:121], v[222:225], v[178:181], v[118:121]
	v_mfma_f32_16x16x32_bf16 v[114:117], v[230:233], v[178:181], v[114:117]
	v_mfma_f32_16x16x32_bf16 v[102:105], v[222:225], v[186:189], v[102:105]
	v_mfma_f32_16x16x32_bf16 v[98:101], v[230:233], v[186:189], v[98:101]
	v_mfma_f32_16x16x32_bf16 v[86:89], v[222:225], v[202:205], v[86:89]
	v_mfma_f32_16x16x32_bf16 v[82:85], v[230:233], v[202:205], v[82:85]
	v_mfma_f32_16x16x32_bf16 v[70:73], v[222:225], v[214:217], v[70:73]
	v_mfma_f32_16x16x32_bf16 v[66:69], v[230:233], v[214:217], v[66:69]
	v_mfma_f32_16x16x32_bf16 v[118:121], v[226:229], v[182:185], v[118:121]
	v_mfma_f32_16x16x32_bf16 v[114:117], v[234:237], v[182:185], v[114:117]
	v_mfma_f32_16x16x32_bf16 v[102:105], v[226:229], v[198:201], v[102:105]
	v_mfma_f32_16x16x32_bf16 v[98:101], v[234:237], v[198:201], v[98:101]
	v_mfma_f32_16x16x32_bf16 v[86:89], v[226:229], v[206:209], v[86:89]
	v_mfma_f32_16x16x32_bf16 v[82:85], v[234:237], v[206:209], v[82:85]
	v_mfma_f32_16x16x32_bf16 v[70:73], v[226:229], v[218:221], v[70:73]
	v_mfma_f32_16x16x32_bf16 v[66:69], v[234:237], v[218:221], v[66:69]
	s_mov_b32 m0, s86
	v_lshl_add_u64 v[162:163], v[238:239], 0, s[70:71]
	s_barrier
	ds_read_b128 v[178:181], v196 offset:49152
	ds_read_b128 v[182:185], v196 offset:50176
	ds_read_b128 v[186:189], v196 offset:51200
	ds_read_b128 v[198:201], v196 offset:52224
	ds_read_b128 v[202:205], v196 offset:53248
	ds_read_b128 v[206:209], v196 offset:54272
	ds_read_b128 v[214:217], v196 offset:55296
	ds_read_b128 v[218:221], v196 offset:56320
	global_load_lds_dwordx4 v[162:163], off
	s_mov_b32 m0, s87
	v_lshl_add_u64 v[162:163], v[240:241], 0, s[70:71]
	global_load_lds_dwordx4 v[162:163], off
	s_barrier
; #define LAS __attribute__((address_space(3)))
;     DEVI f32x4 load(int r, int c) const { const bf16x4 y = *(const bf16x4*)(Y + (size_t)r * DM + c); return (f32x4){bf2f((u16)y[0]), bf2f((u16)y[1]), bf2f((u16)y[2]), bf2f((u16)y[3])}; }
; template <class Epi>
; DEVI void gemm_phase(LAS unsigned char* lds, const Gemm g, const Epi& E) {
;     ...
;             for (int am = 0; am < 4; ++am) {
;                 const int ai = am >> 1, m0 = (am & 1) * 2;
;                 f32x4 pre[2][2][2];
;                 if constexpr (Epi::PRE) {
; #pragma unroll
;                     for (int m = 0; m < 2; ++m)
; #pragma unroll
;                         for (int bj = 0; bj < 2; ++bj)
; #pragma unroll
;                             for (int n = 0; n < 2; ++n) pre[m][bj][n] = E.load(row0 + ai * HALF + (m0 + m) * 16, col0 + bj * HALF + n * NST);
;                 }
; #pragma unroll
;                 for (int mm = 0; mm < 2; ++mm) {
;                     const int m = m0 + mm;
;                     const int r = row0 + ai * HALF + m * 16; float rs = 1.f, part = 0.f;
;                     if constexpr (Epi::RS) rs = rsv[ai * 4 + m];
;                     if constexpr (Epi::PAIR) E.pair8(cur.b, r, cur.pn * HALF + wc * 32 + 8 * fq, acc[ai][0][m][0] * rs, acc[ai][0][m][1] * rs, acc[ai][1][m][0] * rs, acc[ai][1][m][1] * rs);
;                     else
; #pragma unroll
;                     for (int bj = 0; bj < 2; ++bj) {
;                         const int c = col0 + bj * HALF; f32x4 v0 = acc[ai][bj][m][0], v1 = acc[ai][bj][m][1];
;                         if constexpr (Epi::RS) { v0 = v0 * rs; v1 = v1 * rs; }
;                         if constexpr (Epi::PRE) part += E.frag_pre8(cur.b, r, c, v0, v1, pre[mm][bj][0], pre[mm][bj][1]);
;                         else if constexpr (Epi::PERM) E.frag8(cur.b, r, c, v0, v1);
;                         else { E.frag(cur.b, r, c, v0); E.frag(cur.b, r, c + 16, v1); }
;                     }
;                     if constexpr (Epi::SSQ) { part += __shfl_xor(part, 16); part += __shfl_xor(part, 32); if (fq == 0) ((LAS float*)(lds + 131072))[(wr * 4 + wc) * 128 + ai * 64 + m * 16 + fr] = part; }
	s_waitcnt lgkmcnt(0)
	v_mfma_f32_16x16x32_bf16 v[62:65], v[130:133], v[178:181], v[62:65]
	v_mfma_f32_16x16x32_bf16 v[58:61], v[138:141], v[178:181], v[58:61]
	v_mfma_f32_16x16x32_bf16 v[46:49], v[130:133], v[186:189], v[46:49]
	v_mfma_f32_16x16x32_bf16 v[42:45], v[138:141], v[186:189], v[42:45]
	v_mfma_f32_16x16x32_bf16 v[30:33], v[130:133], v[202:205], v[30:33]
	v_mfma_f32_16x16x32_bf16 v[26:29], v[138:141], v[202:205], v[26:29]
	v_mfma_f32_16x16x32_bf16 v[14:17], v[130:133], v[214:217], v[14:17]
	v_mfma_f32_16x16x32_bf16 v[10:13], v[138:141], v[214:217], v[10:13]
	v_mfma_f32_16x16x32_bf16 v[62:65], v[134:137], v[182:185], v[62:65]
	v_mfma_f32_16x16x32_bf16 v[58:61], v[142:145], v[182:185], v[58:61]
	v_mfma_f32_16x16x32_bf16 v[46:49], v[134:137], v[198:201], v[46:49]
	v_mfma_f32_16x16x32_bf16 v[42:45], v[142:145], v[198:201], v[42:45]
	v_mfma_f32_16x16x32_bf16 v[30:33], v[134:137], v[206:209], v[30:33]
	v_mfma_f32_16x16x32_bf16 v[26:29], v[142:145], v[206:209], v[26:29]
	v_mfma_f32_16x16x32_bf16 v[14:17], v[134:137], v[218:221], v[14:17]
	v_mfma_f32_16x16x32_bf16 v[10:13], v[142:145], v[218:221], v[10:13]
	s_barrier
	s_add_u32 s18, s78, 0x40080
	s_addc_u32 s19, s79, 0
	s_add_i32 s26, s27, s82
	s_mov_b32 m0, s26
	v_lshl_add_u64 v[130:131], s[18:19], 0, v[8:9]
	global_load_lds_dwordx4 v[130:131], off
	s_add_i32 m0, s26, 0x2000
	v_lshl_add_u64 v[130:131], s[18:19], 0, v[150:151]
	global_load_lds_dwordx4 v[130:131], off
	s_waitcnt vmcnt(6)
	s_barrier
	v_mfma_f32_16x16x32_bf16 v[54:57], v[222:225], v[178:181], v[54:57]
	v_mfma_f32_16x16x32_bf16 v[50:53], v[230:233], v[178:181], v[50:53]
	v_mfma_f32_16x16x32_bf16 v[38:41], v[222:225], v[186:189], v[38:41]
	v_mfma_f32_16x16x32_bf16 v[34:37], v[230:233], v[186:189], v[34:37]
	v_mfma_f32_16x16x32_bf16 v[22:25], v[222:225], v[202:205], v[22:25]
	v_mfma_f32_16x16x32_bf16 v[18:21], v[230:233], v[202:205], v[18:21]
	v_mfma_f32_16x16x32_bf16 v[4:7], v[222:225], v[214:217], v[4:7]
	v_mfma_f32_16x16x32_bf16 v[0:3], v[230:233], v[214:217], v[0:3]
	v_mfma_f32_16x16x32_bf16 v[54:57], v[226:229], v[182:185], v[54:57]
	v_mfma_f32_16x16x32_bf16 v[50:53], v[234:237], v[182:185], v[50:53]
	v_mfma_f32_16x16x32_bf16 v[38:41], v[226:229], v[198:201], v[38:41]
	v_mfma_f32_16x16x32_bf16 v[34:37], v[234:237], v[198:201], v[34:37]
	v_mfma_f32_16x16x32_bf16 v[22:25], v[226:229], v[206:209], v[22:25]
	v_mfma_f32_16x16x32_bf16 v[18:21], v[234:237], v[206:209], v[18:21]
	v_mfma_f32_16x16x32_bf16 v[4:7], v[226:229], v[218:221], v[4:7]
	v_mfma_f32_16x16x32_bf16 v[0:3], v[234:237], v[218:221], v[0:3]
	s_add_i32 s17, s17, 2
	s_add_u32 s8, s8, 0x100
	s_addc_u32 s9, s9, 0
	s_add_u32 s13, s13, 0x100
	s_addc_u32 s15, s15, 0
	s_cmp_gt_u32 s17, 13
	s_barrier
	s_cbranch_scc0 .LBB0_1595
	s_setprio 0
	s_lshl_b32 s0, s68, 8
	v_add_u32_e32 v182, s0, v190
	v_lshl_or_b32 v180, s12, 8, v195
	v_ashrrev_i32_e32 v183, 31, v182
	v_lshlrev_b64 v[130:131], 12, v[182:183]
	v_ashrrev_i32_e32 v181, 31, v180
	v_lshl_add_u64 v[130:131], s[30:31], 0, v[130:131]
	v_lshlrev_b64 v[184:185], 2, v[180:181]
	v_lshl_add_u64 v[162:163], v[130:131], 0, v[184:185]
	global_load_dwordx4 v[200:203], v[162:163], off nt
	global_load_dwordx4 v[204:207], v[162:163], off offset:16 nt
	global_load_dwordx4 v[214:217], v[162:163], off offset:512 nt
	global_load_dwordx4 v[218:221], v[162:163], off offset:528 nt
	v_or_b32_e32 v188, 16, v182
	v_ashrrev_i32_e32 v189, 31, v188
	v_lshlrev_b64 v[130:131], 12, v[188:189]
	v_lshl_add_u64 v[130:131], s[30:31], 0, v[130:131]
	v_lshl_add_u64 v[186:187], v[130:131], 0, v[184:185]
	global_load_dwordx4 v[138:141], v[186:187], off offset:16 nt
	global_load_dwordx4 v[142:145], v[186:187], off nt
	global_load_dwordx4 v[130:133], v[186:187], off offset:528 nt
	global_load_dwordx4 v[134:137], v[186:187], off offset:512 nt
	v_and_b32_e32 v165, 64, v155
	v_xor_b32_e32 v164, 16, v155
	v_add_u32_e32 v165, 64, v165
	v_xor_b32_e32 v179, 32, v155
	v_cmp_lt_i32_e32 vcc, v164, v165
	v_or_b32_e32 v178, 0x80, v180
	s_waitcnt vmcnt(0)
	v_pk_add_f32 v[128:129], v[128:129], v[202:203]
	v_cndmask_b32_e32 v164, v155, v164, vcc
	v_cmp_lt_i32_e32 vcc, v179, v165
	v_lshlrev_b32_e32 v198, 2, v164
	v_pk_add_f32 v[126:127], v[126:127], v[200:201]
	v_cndmask_b32_e32 v165, v155, v179, vcc
	v_lshlrev_b32_e32 v197, 2, v165
	v_lshlrev_b64 v[164:165], 10, v[182:183]
	v_pk_add_f32 v[124:125], v[124:125], v[206:207]
	v_pk_add_f32 v[122:123], v[122:123], v[204:205]
	v_pk_add_f32 v[120:121], v[120:121], v[216:217]
	v_pk_add_f32 v[118:119], v[118:119], v[214:215]
	v_pk_add_f32 v[202:203], v[116:117], v[220:221]
	v_pk_add_f32 v[200:201], v[114:115], v[218:219]
	v_lshl_add_u64 v[208:209], v[164:165], 0, v[180:181]
	global_store_dwordx4 v[162:163], v[126:129], off nt
	global_store_dwordx4 v[162:163], v[122:125], off offset:16 nt
	v_cvt_pk_bf16_f32 v114, v126, v127
	v_cvt_pk_bf16_f32 v115, v128, v129
	v_cvt_pk_bf16_f32 v116, v122, v123
	v_cvt_pk_bf16_f32 v117, v124, v125
	v_mul_f32_e32 v127, v127, v127
	v_mul_f32_e32 v129, v129, v129
	v_mul_f32_e32 v123, v123, v123
	v_mul_f32_e32 v125, v125, v125
	v_mul_f32_e32 v183, v119, v119
	v_mul_f32_e32 v199, v121, v121
	v_mul_f32_e32 v204, v201, v201
	v_mul_f32_e32 v205, v203, v203
	v_lshl_add_u64 v[208:209], v[208:209], 1, s[24:25]
	v_fmac_f32_e32 v127, v126, v126
	v_fmac_f32_e32 v129, v128, v128
	v_fmac_f32_e32 v123, v122, v122
	v_fmac_f32_e32 v125, v124, v124
	v_fmac_f32_e32 v183, v118, v118
	v_fmac_f32_e32 v199, v120, v120
	v_fmac_f32_e32 v204, v200, v200
	v_fmac_f32_e32 v205, v202, v202
	global_store_dwordx4 v[208:209], v[114:117], off
	v_ashrrev_i32_e32 v179, 31, v178
	v_lshl_add_u64 v[164:165], v[164:165], 0, v[178:179]
	v_add_f32_e32 v114, v127, v129
	v_add_f32_e32 v115, v123, v125
	v_add_f32_e32 v116, v183, v199
	v_add_f32_e32 v117, v204, v205
	v_add_f32_e32 v114, v114, v115
	v_add_f32_e32 v115, v116, v117
	v_add_f32_e32 v114, v114, v115
	ds_bpermute_b32 v115, v198, v114
	global_store_dwordx4 v[162:163], v[118:121], off offset:512 nt
	global_store_dwordx4 v[162:163], v[200:203], off offset:528 nt
	v_cvt_pk_bf16_f32 v116, v118, v119
	v_cvt_pk_bf16_f32 v117, v120, v121
	v_cvt_pk_bf16_f32 v118, v200, v201
	s_waitcnt lgkmcnt(0)
	v_add_f32_e32 v114, v114, v115
	ds_bpermute_b32 v115, v197, v114
	v_cvt_pk_bf16_f32 v119, v202, v203
	v_lshl_add_u64 v[120:121], v[164:165], 1, s[24:25]
	global_store_dwordx4 v[120:121], v[116:119], off
	s_and_saveexec_b64 s[8:9], s[2:3]
	s_cbranch_execz .LBB0_1598
	s_waitcnt lgkmcnt(0)
	v_add_f32_e32 v114, v114, v115
	ds_write_b32 v192, v114

; #define LAS __attribute__((address_space(3)))
;     DEVI f32x4 load(int r, int c) const { const bf16x4 y = *(const bf16x4*)(Y + (size_t)r * DM + c); return (f32x4){bf2f((u16)y[0]), bf2f((u16)y[1]), bf2f((u16)y[2]), bf2f((u16)y[3])}; }
; template <class Epi>
; DEVI void gemm_phase(LAS unsigned char* lds, const Gemm g, const Epi& E) {
;     ...
;             for (int am = 0; am < 4; ++am) {
;                 const int ai = am >> 1, m0 = (am & 1) * 2;
;                 f32x4 pre[2][2][2];
;                 if constexpr (Epi::PRE) {
; #pragma unroll
;                     for (int m = 0; m < 2; ++m)
; #pragma unroll
;                         for (int bj = 0; bj < 2; ++bj)
; #pragma unroll
;                             for (int n = 0; n < 2; ++n) pre[m][bj][n] = E.load(row0 + ai * HALF + (m0 + m) * 16, col0 + bj * HALF + n * NST);
;                 }
; #pragma unroll
;                 for (int mm = 0; mm < 2; ++mm) {
;                     const int m = m0 + mm;
;                     const int r = row0 + ai * HALF + m * 16; float rs = 1.f, part = 0.f;
;                     if constexpr (Epi::RS) rs = rsv[ai * 4 + m];
;                     if constexpr (Epi::PAIR) E.pair8(cur.b, r, cur.pn * HALF + wc * 32 + 8 * fq, acc[ai][0][m][0] * rs, acc[ai][0][m][1] * rs, acc[ai][1][m][0] * rs, acc[ai][1][m][1] * rs);
;                     else
; #pragma unroll
;                     for (int bj = 0; bj < 2; ++bj) {
;                         const int c = col0 + bj * HALF; f32x4 v0 = acc[ai][bj][m][0], v1 = acc[ai][bj][m][1];
;                         if constexpr (Epi::RS) { v0 = v0 * rs; v1 = v1 * rs; }
;                         if constexpr (Epi::PRE) part += E.frag_pre8(cur.b, r, c, v0, v1, pre[mm][bj][0], pre[mm][bj][1]);
;                         else if constexpr (Epi::PERM) E.frag8(cur.b, r, c, v0, v1);
;                         else { E.frag(cur.b, r, c, v0); E.frag(cur.b, r, c + 16, v1); }
;                     }
;                     if constexpr (Epi::SSQ) { part += __shfl_xor(part, 16); part += __shfl_xor(part, 32); if (fq == 0) ((LAS float*)(lds + 131072))[(wr * 4 + wc) * 128 + ai * 64 + m * 16 + fr] = part; }
.LBB0_1600:
	s_or_b64 exec, exec, s[8:9]
	v_or_b32_e32 v134, 32, v182
	v_ashrrev_i32_e32 v135, 31, v134
	s_waitcnt lgkmcnt(0)
	v_lshlrev_b64 v[98:99], 12, v[134:135]
	v_lshl_add_u64 v[98:99], s[30:31], 0, v[98:99]
	v_lshl_add_u64 v[136:137], v[98:99], 0, v[184:185]
	global_load_dwordx4 v[118:121], v[136:137], off nt
	global_load_dwordx4 v[122:125], v[136:137], off offset:16 nt
	global_load_dwordx4 v[126:129], v[136:137], off offset:512 nt
	global_load_dwordx4 v[130:133], v[136:137], off offset:528 nt
	v_or_b32_e32 v116, 48, v182
	v_ashrrev_i32_e32 v117, 31, v116
	v_lshlrev_b64 v[98:99], 12, v[116:117]
	v_lshl_add_u64 v[98:99], s[30:31], 0, v[98:99]
	v_lshl_add_u64 v[114:115], v[98:99], 0, v[184:185]
	global_load_dwordx4 v[106:109], v[114:115], off offset:16 nt
	global_load_dwordx4 v[110:113], v[114:115], off nt
	global_load_dwordx4 v[98:101], v[114:115], off offset:528 nt
	global_load_dwordx4 v[102:105], v[114:115], off offset:512 nt
	v_lshlrev_b64 v[134:135], 10, v[134:135]
	v_lshl_add_u64 v[138:139], v[134:135], 0, v[180:181]
	v_lshl_add_u64 v[138:139], v[138:139], 1, s[24:25]
	v_lshl_add_u64 v[134:135], v[134:135], 0, v[178:179]
	s_waitcnt vmcnt(7)
	v_pk_add_f32 v[96:97], v[96:97], v[120:121]
	v_pk_add_f32 v[94:95], v[94:95], v[118:119]
	s_waitcnt vmcnt(6)
	v_pk_add_f32 v[92:93], v[92:93], v[124:125]
	v_pk_add_f32 v[90:91], v[90:91], v[122:123]
	s_waitcnt vmcnt(5)
	v_pk_add_f32 v[88:89], v[88:89], v[128:129]
	v_pk_add_f32 v[86:87], v[86:87], v[126:127]
	s_waitcnt vmcnt(4)
	v_pk_add_f32 v[120:121], v[84:85], v[132:133]
	v_pk_add_f32 v[118:119], v[82:83], v[130:131]
	global_store_dwordx4 v[136:137], v[94:97], off nt
	global_store_dwordx4 v[136:137], v[90:93], off offset:16 nt
	v_cvt_pk_bf16_f32 v82, v94, v95
	v_cvt_pk_bf16_f32 v83, v96, v97
	v_cvt_pk_bf16_f32 v84, v90, v91
	v_cvt_pk_bf16_f32 v85, v92, v93
	v_mul_f32_e32 v95, v95, v95
	v_mul_f32_e32 v97, v97, v97
	v_mul_f32_e32 v91, v91, v91
	v_mul_f32_e32 v93, v93, v93
	v_mul_f32_e32 v122, v87, v87
	v_mul_f32_e32 v123, v89, v89
	v_mul_f32_e32 v124, v119, v119
	v_mul_f32_e32 v125, v121, v121
	v_fmac_f32_e32 v95, v94, v94
	v_fmac_f32_e32 v97, v96, v96
	v_fmac_f32_e32 v91, v90, v90
	v_fmac_f32_e32 v93, v92, v92
	v_fmac_f32_e32 v122, v86, v86
	v_fmac_f32_e32 v123, v88, v88
	v_fmac_f32_e32 v124, v118, v118
	v_fmac_f32_e32 v125, v120, v120
	global_store_dwordx4 v[138:139], v[82:85], off
	global_store_dwordx4 v[136:137], v[86:89], off offset:512 nt
	global_store_dwordx4 v[136:137], v[118:121], off offset:528 nt
	v_add_f32_e32 v82, v95, v97
	v_add_f32_e32 v83, v91, v93
	v_add_f32_e32 v84, v122, v123
	v_add_f32_e32 v85, v124, v125
	v_add_f32_e32 v82, v82, v83
	v_add_f32_e32 v83, v84, v85
	v_add_f32_e32 v82, v82, v83
	ds_bpermute_b32 v83, v198, v82
	v_cvt_pk_bf16_f32 v84, v86, v87
	v_cvt_pk_bf16_f32 v85, v88, v89
	v_cvt_pk_bf16_f32 v86, v118, v119
	v_cvt_pk_bf16_f32 v87, v120, v121
	s_waitcnt lgkmcnt(0)
	v_add_f32_e32 v82, v82, v83
	ds_bpermute_b32 v83, v197, v82
	v_lshl_add_u64 v[88:89], v[134:135], 1, s[24:25]
	global_store_dwordx4 v[88:89], v[84:87], off
	s_and_saveexec_b64 s[8:9], s[2:3]
	s_cbranch_execz .LBB0_1602
	s_waitcnt lgkmcnt(0)
	v_add_f32_e32 v82, v82, v83
	ds_write_b32 v192, v82 offset:128

; #define LAS __attribute__((address_space(3)))
;     DEVI f32x4 load(int r, int c) const { const bf16x4 y = *(const bf16x4*)(Y + (size_t)r * DM + c); return (f32x4){bf2f((u16)y[0]), bf2f((u16)y[1]), bf2f((u16)y[2]), bf2f((u16)y[3])}; }
; template <class Epi>
; DEVI void gemm_phase(LAS unsigned char* lds, const Gemm g, const Epi& E) {
;     ...
;             for (int am = 0; am < 4; ++am) {
;                 const int ai = am >> 1, m0 = (am & 1) * 2;
;                 f32x4 pre[2][2][2];
;                 if constexpr (Epi::PRE) {
; #pragma unroll
;                     for (int m = 0; m < 2; ++m)
; #pragma unroll
;                         for (int bj = 0; bj < 2; ++bj)
; #pragma unroll
;                             for (int n = 0; n < 2; ++n) pre[m][bj][n] = E.load(row0 + ai * HALF + (m0 + m) * 16, col0 + bj * HALF + n * NST);
;                 }
; #pragma unroll
;                 for (int mm = 0; mm < 2; ++mm) {
;                     const int m = m0 + mm;
;                     const int r = row0 + ai * HALF + m * 16; float rs = 1.f, part = 0.f;
;                     if constexpr (Epi::RS) rs = rsv[ai * 4 + m];
;                     if constexpr (Epi::PAIR) E.pair8(cur.b, r, cur.pn * HALF + wc * 32 + 8 * fq, acc[ai][0][m][0] * rs, acc[ai][0][m][1] * rs, acc[ai][1][m][0] * rs, acc[ai][1][m][1] * rs);
;                     else
; #pragma unroll
;                     for (int bj = 0; bj < 2; ++bj) {
;                         const int c = col0 + bj * HALF; f32x4 v0 = acc[ai][bj][m][0], v1 = acc[ai][bj][m][1];
;                         if constexpr (Epi::RS) { v0 = v0 * rs; v1 = v1 * rs; }
;                         if constexpr (Epi::PRE) part += E.frag_pre8(cur.b, r, c, v0, v1, pre[mm][bj][0], pre[mm][bj][1]);
;                         else if constexpr (Epi::PERM) E.frag8(cur.b, r, c, v0, v1);
;                         else { E.frag(cur.b, r, c, v0); E.frag(cur.b, r, c + 16, v1); }
;                     }
;                     if constexpr (Epi::SSQ) { part += __shfl_xor(part, 16); part += __shfl_xor(part, 32); if (fq == 0) ((LAS float*)(lds + 131072))[(wr * 4 + wc) * 128 + ai * 64 + m * 16 + fr] = part; }
.LBB0_1604:
	s_or_b64 exec, exec, s[8:9]
	v_add_u32_e32 v102, 0x80, v182
	v_ashrrev_i32_e32 v103, 31, v102
	s_waitcnt lgkmcnt(0)
	v_lshlrev_b64 v[66:67], 12, v[102:103]
	v_lshl_add_u64 v[66:67], s[30:31], 0, v[66:67]
	v_lshl_add_u64 v[104:105], v[66:67], 0, v[184:185]
	global_load_dwordx4 v[86:89], v[104:105], off nt
	global_load_dwordx4 v[90:93], v[104:105], off offset:16 nt
	global_load_dwordx4 v[94:97], v[104:105], off offset:512 nt
	global_load_dwordx4 v[98:101], v[104:105], off offset:528 nt
	v_add_u32_e32 v84, 0x90, v182
	v_ashrrev_i32_e32 v85, 31, v84
	v_lshlrev_b64 v[66:67], 12, v[84:85]
	v_lshl_add_u64 v[66:67], s[30:31], 0, v[66:67]
	v_lshl_add_u64 v[82:83], v[66:67], 0, v[184:185]
	global_load_dwordx4 v[74:77], v[82:83], off offset:16 nt
	global_load_dwordx4 v[78:81], v[82:83], off nt
	global_load_dwordx4 v[66:69], v[82:83], off offset:528 nt
	global_load_dwordx4 v[70:73], v[82:83], off offset:512 nt
	v_lshlrev_b64 v[102:103], 10, v[102:103]
	v_lshl_add_u64 v[106:107], v[102:103], 0, v[180:181]
	v_lshl_add_u64 v[106:107], v[106:107], 1, s[24:25]
	v_lshl_add_u64 v[102:103], v[102:103], 0, v[178:179]
	s_waitcnt vmcnt(7)
	v_pk_add_f32 v[64:65], v[64:65], v[88:89]
	v_pk_add_f32 v[62:63], v[62:63], v[86:87]
	s_waitcnt vmcnt(6)
	v_pk_add_f32 v[60:61], v[60:61], v[92:93]
	v_pk_add_f32 v[58:59], v[58:59], v[90:91]
	s_waitcnt vmcnt(5)
	v_pk_add_f32 v[56:57], v[56:57], v[96:97]
	v_pk_add_f32 v[54:55], v[54:55], v[94:95]
	s_waitcnt vmcnt(4)
	v_pk_add_f32 v[88:89], v[52:53], v[100:101]
	v_pk_add_f32 v[86:87], v[50:51], v[98:99]
	global_store_dwordx4 v[104:105], v[62:65], off nt
	global_store_dwordx4 v[104:105], v[58:61], off offset:16 nt
	v_cvt_pk_bf16_f32 v50, v62, v63
	v_cvt_pk_bf16_f32 v51, v64, v65
	v_cvt_pk_bf16_f32 v52, v58, v59
	v_cvt_pk_bf16_f32 v53, v60, v61
	v_mul_f32_e32 v63, v63, v63
	v_mul_f32_e32 v65, v65, v65
	v_mul_f32_e32 v59, v59, v59
	v_mul_f32_e32 v61, v61, v61
	v_mul_f32_e32 v90, v55, v55
	v_mul_f32_e32 v91, v57, v57
	v_mul_f32_e32 v92, v87, v87
	v_mul_f32_e32 v93, v89, v89
	v_fmac_f32_e32 v63, v62, v62
	v_fmac_f32_e32 v65, v64, v64
	v_fmac_f32_e32 v59, v58, v58
	v_fmac_f32_e32 v61, v60, v60
	v_fmac_f32_e32 v90, v54, v54
	v_fmac_f32_e32 v91, v56, v56
	v_fmac_f32_e32 v92, v86, v86
	v_fmac_f32_e32 v93, v88, v88
	global_store_dwordx4 v[106:107], v[50:53], off
	global_store_dwordx4 v[104:105], v[54:57], off offset:512 nt
	global_store_dwordx4 v[104:105], v[86:89], off offset:528 nt
	v_add_f32_e32 v50, v63, v65
	v_add_f32_e32 v51, v59, v61
	v_add_f32_e32 v52, v90, v91
	v_add_f32_e32 v53, v92, v93
	v_add_f32_e32 v50, v50, v51
	v_add_f32_e32 v51, v52, v53
	v_add_f32_e32 v50, v50, v51
	ds_bpermute_b32 v51, v198, v50
	v_cvt_pk_bf16_f32 v52, v54, v55
	v_cvt_pk_bf16_f32 v53, v56, v57
	v_cvt_pk_bf16_f32 v54, v86, v87
	v_cvt_pk_bf16_f32 v55, v88, v89
	s_waitcnt lgkmcnt(0)
	v_add_f32_e32 v50, v50, v51
	ds_bpermute_b32 v51, v197, v50
	v_lshl_add_u64 v[56:57], v[102:103], 1, s[24:25]
	global_store_dwordx4 v[56:57], v[52:55], off
	s_and_saveexec_b64 s[8:9], s[2:3]
	s_cbranch_execz .LBB0_1606
	s_waitcnt lgkmcnt(0)
	v_add_f32_e32 v50, v50, v51
	ds_write_b32 v192, v50 offset:256

; #define LAS __attribute__((address_space(3)))
;     DEVI f32x4 load(int r, int c) const { const bf16x4 y = *(const bf16x4*)(Y + (size_t)r * DM + c); return (f32x4){bf2f((u16)y[0]), bf2f((u16)y[1]), bf2f((u16)y[2]), bf2f((u16)y[3])}; }
; template <class Epi>
; DEVI void gemm_phase(LAS unsigned char* lds, const Gemm g, const Epi& E) {
;     ...
;             for (int am = 0; am < 4; ++am) {
;                 const int ai = am >> 1, m0 = (am & 1) * 2;
;                 f32x4 pre[2][2][2];
;                 if constexpr (Epi::PRE) {
; #pragma unroll
;                     for (int m = 0; m < 2; ++m)
; #pragma unroll
;                         for (int bj = 0; bj < 2; ++bj)
; #pragma unroll
;                             for (int n = 0; n < 2; ++n) pre[m][bj][n] = E.load(row0 + ai * HALF + (m0 + m) * 16, col0 + bj * HALF + n * NST);
;                 }
; #pragma unroll
;                 for (int mm = 0; mm < 2; ++mm) {
;                     const int m = m0 + mm;
;                     const int r = row0 + ai * HALF + m * 16; float rs = 1.f, part = 0.f;
;                     if constexpr (Epi::RS) rs = rsv[ai * 4 + m];
;                     if constexpr (Epi::PAIR) E.pair8(cur.b, r, cur.pn * HALF + wc * 32 + 8 * fq, acc[ai][0][m][0] * rs, acc[ai][0][m][1] * rs, acc[ai][1][m][0] * rs, acc[ai][1][m][1] * rs);
;                     else
; #pragma unroll
;                     for (int bj = 0; bj < 2; ++bj) {
;                         const int c = col0 + bj * HALF; f32x4 v0 = acc[ai][bj][m][0], v1 = acc[ai][bj][m][1];
;                         if constexpr (Epi::RS) { v0 = v0 * rs; v1 = v1 * rs; }
;                         if constexpr (Epi::PRE) part += E.frag_pre8(cur.b, r, c, v0, v1, pre[mm][bj][0], pre[mm][bj][1]);
;                         else if constexpr (Epi::PERM) E.frag8(cur.b, r, c, v0, v1);
;                         else { E.frag(cur.b, r, c, v0); E.frag(cur.b, r, c + 16, v1); }
;                     }
;                     if constexpr (Epi::SSQ) { part += __shfl_xor(part, 16); part += __shfl_xor(part, 32); if (fq == 0) ((LAS float*)(lds + 131072))[(wr * 4 + wc) * 128 + ai * 64 + m * 16 + fr] = part; }
.LBB0_1608:
	s_or_b64 exec, exec, s[8:9]
	v_add_u32_e32 v70, 0xa0, v182
	v_ashrrev_i32_e32 v71, 31, v70
	s_waitcnt lgkmcnt(0)
	v_lshlrev_b64 v[34:35], 12, v[70:71]
	v_lshl_add_u64 v[34:35], s[30:31], 0, v[34:35]
	v_lshl_add_u64 v[72:73], v[34:35], 0, v[184:185]
	global_load_dwordx4 v[54:57], v[72:73], off nt
	global_load_dwordx4 v[58:61], v[72:73], off offset:16 nt
	global_load_dwordx4 v[62:65], v[72:73], off offset:512 nt
	global_load_dwordx4 v[66:69], v[72:73], off offset:528 nt
	v_add_u32_e32 v52, 0xb0, v182
	v_ashrrev_i32_e32 v53, 31, v52
	v_lshlrev_b64 v[34:35], 12, v[52:53]
	v_lshl_add_u64 v[34:35], s[30:31], 0, v[34:35]
	v_lshl_add_u64 v[50:51], v[34:35], 0, v[184:185]
	global_load_dwordx4 v[42:45], v[50:51], off offset:16 nt
	global_load_dwordx4 v[46:49], v[50:51], off nt
	global_load_dwordx4 v[34:37], v[50:51], off offset:528 nt
	global_load_dwordx4 v[38:41], v[50:51], off offset:512 nt
	v_lshlrev_b64 v[70:71], 10, v[70:71]
	v_lshl_add_u64 v[74:75], v[70:71], 0, v[180:181]
	v_lshl_add_u64 v[74:75], v[74:75], 1, s[24:25]
	v_lshl_add_u64 v[70:71], v[70:71], 0, v[178:179]
	s_waitcnt vmcnt(7)
	v_pk_add_f32 v[32:33], v[32:33], v[56:57]
	v_pk_add_f32 v[30:31], v[30:31], v[54:55]
	s_waitcnt vmcnt(6)
	v_pk_add_f32 v[28:29], v[28:29], v[60:61]
	v_pk_add_f32 v[26:27], v[26:27], v[58:59]
	s_waitcnt vmcnt(5)
	v_pk_add_f32 v[24:25], v[24:25], v[64:65]
	v_pk_add_f32 v[22:23], v[22:23], v[62:63]
	s_waitcnt vmcnt(4)
	v_pk_add_f32 v[56:57], v[20:21], v[68:69]
	v_pk_add_f32 v[54:55], v[18:19], v[66:67]
	global_store_dwordx4 v[72:73], v[30:33], off nt
	global_store_dwordx4 v[72:73], v[26:29], off offset:16 nt
	v_cvt_pk_bf16_f32 v18, v30, v31
	v_cvt_pk_bf16_f32 v19, v32, v33
	v_cvt_pk_bf16_f32 v20, v26, v27
	v_cvt_pk_bf16_f32 v21, v28, v29
	v_mul_f32_e32 v31, v31, v31
	v_mul_f32_e32 v33, v33, v33
	v_mul_f32_e32 v27, v27, v27
	v_mul_f32_e32 v29, v29, v29
	v_mul_f32_e32 v58, v23, v23
	v_mul_f32_e32 v59, v25, v25
	v_mul_f32_e32 v60, v55, v55
	v_mul_f32_e32 v61, v57, v57
	v_fmac_f32_e32 v31, v30, v30
	v_fmac_f32_e32 v33, v32, v32
	v_fmac_f32_e32 v27, v26, v26
	v_fmac_f32_e32 v29, v28, v28
	v_fmac_f32_e32 v58, v22, v22
	v_fmac_f32_e32 v59, v24, v24
	v_fmac_f32_e32 v60, v54, v54
	v_fmac_f32_e32 v61, v56, v56
	global_store_dwordx4 v[74:75], v[18:21], off
	global_store_dwordx4 v[72:73], v[22:25], off offset:512 nt
	global_store_dwordx4 v[72:73], v[54:57], off offset:528 nt
	v_add_f32_e32 v18, v31, v33
	v_add_f32_e32 v19, v27, v29
	v_add_f32_e32 v20, v58, v59
	v_add_f32_e32 v21, v60, v61
	v_add_f32_e32 v18, v18, v19
	v_add_f32_e32 v19, v20, v21
	v_add_f32_e32 v18, v18, v19
	ds_bpermute_b32 v19, v198, v18
	v_cvt_pk_bf16_f32 v20, v22, v23
	v_cvt_pk_bf16_f32 v21, v24, v25
	v_cvt_pk_bf16_f32 v22, v54, v55
	v_cvt_pk_bf16_f32 v23, v56, v57
	s_waitcnt lgkmcnt(0)
	v_add_f32_e32 v18, v18, v19
	ds_bpermute_b32 v19, v197, v18
	v_lshl_add_u64 v[24:25], v[70:71], 1, s[24:25]
	global_store_dwordx4 v[24:25], v[20:23], off
	s_and_saveexec_b64 s[8:9], s[2:3]
	s_cbranch_execz .LBB0_1610
	s_waitcnt lgkmcnt(0)
	v_add_f32_e32 v18, v18, v19
	ds_write_b32 v192, v18 offset:384

; #define PG8_STAGE(bufoff, gbase, voff) do { _Pragma("unroll") for (int _i = 0; _i < 2; ++_i) \
;         __builtin_amdgcn_global_load_lds((const unsigned*)((const char*)(gbase) + (voff)[_i]), (LAS unsigned*)(lds + (bufoff) + ldsw + _i * 8192), 16, 0, 0); } while (0)
; #define PG8_LDA(dst, b, h) do { _Pragma("unroll") for (int m = 0; m < 4; ++m) _Pragma("unroll") for (int k = 0; k < 2; ++k) dst[m][k] = *(const LAS bf16x8*)(lds + PG8_SA(b, h) + aoff + m * 2048 + k * 1024); } while (0)
; #define PG8_LDB(dst, b, h) do { _Pragma("unroll") for (int n = 0; n < 2; ++n) _Pragma("unroll") for (int k = 0; k < 2; ++k) dst[n][k] = *(const LAS bf16x8*)(lds + PG8_SB(b, h) + boff + n * 2048 + k * 1024); } while (0)
; #define PG8_MMA(ai, bj, At, Bt) do { __builtin_amdgcn_s_setprio(1); _Pragma("unroll") for (int m = 0; m < 4; ++m) _Pragma("unroll") for (int n = 0; n < 2; ++n) _Pragma("unroll") for (int k = 0; k < 2; ++k) \
;         acc[ai][bj][m][n] = __builtin_amdgcn_mfma_f32_16x16x32_bf16(Bt[n][k], At[m][k], acc[ai][bj][m][n], 0, 0, 0); __builtin_amdgcn_s_setprio(0); } while (0)
; #define PG8_WAIT_L(n) asm volatile("s_waitcnt lgkmcnt(" #n ")" ::: "memory")
; #define PG8_BAR __builtin_amdgcn_s_barrier()
; #define PG8_SCHED __builtin_amdgcn_sched_barrier(0)
; template <class Epi>
; DEVI void gemm_phase(LAS unsigned char* lds, const Gemm g, const Epi& E) {
;     ...
;         for (int t = 0; t < nt; t += 2) {
;             const bool last = (t == nt - 2);
;             const char* a1 = cA + (size_t)(t + 1) * kstep;
;             const char* a2 = last ? nA : cA + (size_t)(t + 2) * kstep; const char* b2 = last ? nB : cB + (size_t)(t + 2) * kstep;
;             const char* a3 = a2 + kstep; const char* b3 = b2 + kstep;
;             PG8_LDB(B0, 0, 0); PG8_SCHED; PG8_LDA(At, 0, 0); PG8_STAGE(PG8_SA(1, 1), a1 + hstepA, voffA);
;             PG8_WAIT_L(8); PG8_BAR; PG8_WAIT_L(0); PG8_MMA(0, 0, At, B0); PG8_BAR; PG8_SCHED;
;             PG8_LDB(B1, 0, 1); PG8_STAGE(PG8_SB(0, 0), b2, voffB);
;             PG8_BAR; PG8_WAIT_L(0); PG8_MMA(0, 1, At, B1); PG8_BAR;
;             PG8_LDA(At, 0, 1); PG8_STAGE(PG8_SA(0, 0), a2, voffA);
;             PG8_BAR; PG8_WAIT_L(0); PG8_MMA(1, 0, At, B0); PG8_BAR; PG8_SCHED;
.LBB0_1747:
	s_add_u32 s36, s16, 0x100
	s_addc_u32 s37, s17, 0
	s_add_i32 s19, 0, 0x10000
	v_add_u32_e32 v142, s19, v191
	ds_read_b128 v[130:133], v142
	ds_read_b128 v[134:137], v142 offset:1024
	ds_read_b128 v[138:141], v142 offset:2048
	ds_read_b128 v[142:145], v142 offset:3072
	s_cmp_eq_u32 s18, 40
	s_cselect_b32 s69, s9, s37
	s_cselect_b32 s68, s8, s36
	s_cselect_b32 s47, s11, s13
	s_cselect_b32 s46, s10, s1
	v_lshl_add_u64 v[162:163], s[16:17], 0, v[152:153]
	s_add_i32 m0, s81, 0xc000
	ds_read_b128 v[178:181], v196
	ds_read_b128 v[182:185], v196 offset:1024
	ds_read_b128 v[186:189], v196 offset:2048
	ds_read_b128 v[198:201], v196 offset:3072
	ds_read_b128 v[202:205], v196 offset:4096
	ds_read_b128 v[206:209], v196 offset:5120
	ds_read_b128 v[214:217], v196 offset:6144
	ds_read_b128 v[218:221], v196 offset:7168
	global_load_lds_dwordx4 v[162:163], off
	s_add_i32 m0, s81, 0xe000
	v_lshl_add_u64 v[162:163], s[16:17], 0, v[176:177]
	global_load_lds_dwordx4 v[162:163], off
	s_waitcnt lgkmcnt(8)
	s_barrier
	s_waitcnt lgkmcnt(0)
	v_mfma_f32_16x16x32_bf16 v[126:129], v[130:133], v[178:181], v[126:129]
	v_mfma_f32_16x16x32_bf16 v[122:125], v[138:141], v[178:181], v[122:125]
	v_mfma_f32_16x16x32_bf16 v[110:113], v[130:133], v[186:189], v[110:113]
	v_mfma_f32_16x16x32_bf16 v[106:109], v[138:141], v[186:189], v[106:109]
	v_mfma_f32_16x16x32_bf16 v[94:97], v[130:133], v[202:205], v[94:97]
	v_mfma_f32_16x16x32_bf16 v[90:93], v[138:141], v[202:205], v[90:93]
	v_mfma_f32_16x16x32_bf16 v[78:81], v[130:133], v[214:217], v[78:81]
	v_mfma_f32_16x16x32_bf16 v[74:77], v[138:141], v[214:217], v[74:77]
	v_mfma_f32_16x16x32_bf16 v[126:129], v[134:137], v[182:185], v[126:129]
	v_mfma_f32_16x16x32_bf16 v[122:125], v[142:145], v[182:185], v[122:125]
	v_mfma_f32_16x16x32_bf16 v[110:113], v[134:137], v[198:201], v[110:113]
	v_mfma_f32_16x16x32_bf16 v[106:109], v[142:145], v[198:201], v[106:109]
	v_mfma_f32_16x16x32_bf16 v[94:97], v[134:137], v[206:209], v[94:97]
	v_mfma_f32_16x16x32_bf16 v[90:93], v[142:145], v[206:209], v[90:93]
	v_mfma_f32_16x16x32_bf16 v[78:81], v[134:137], v[218:221], v[78:81]
	v_mfma_f32_16x16x32_bf16 v[74:77], v[142:145], v[218:221], v[74:77]
	s_barrier
	s_add_i32 s26, 0, 0x14000
	v_add_u32_e32 v162, s26, v191
	s_add_i32 s16, s19, s80
	ds_read_b128 v[222:225], v162
	ds_read_b128 v[226:229], v162 offset:1024
	ds_read_b128 v[230:233], v162 offset:2048
	ds_read_b128 v[234:237], v162 offset:3072
	v_lshl_add_u64 v[162:163], s[46:47], 0, v[8:9]
	s_mov_b32 m0, s16
	v_lshl_add_u64 v[164:165], s[46:47], 0, v[150:151]
	global_load_lds_dwordx4 v[162:163], off
	s_add_i32 m0, s16, 0x2000
	s_nop 0
	global_load_lds_dwordx4 v[164:165], off
	s_barrier
	s_waitcnt lgkmcnt(0)
	v_mfma_f32_16x16x32_bf16 v[118:121], v[222:225], v[178:181], v[118:121]
	v_mfma_f32_16x16x32_bf16 v[114:117], v[230:233], v[178:181], v[114:117]
	v_mfma_f32_16x16x32_bf16 v[102:105], v[222:225], v[186:189], v[102:105]
	v_mfma_f32_16x16x32_bf16 v[98:101], v[230:233], v[186:189], v[98:101]
	v_mfma_f32_16x16x32_bf16 v[86:89], v[222:225], v[202:205], v[86:89]
	v_mfma_f32_16x16x32_bf16 v[82:85], v[230:233], v[202:205], v[82:85]
	v_mfma_f32_16x16x32_bf16 v[70:73], v[222:225], v[214:217], v[70:73]
	v_mfma_f32_16x16x32_bf16 v[66:69], v[230:233], v[214:217], v[66:69]
	v_mfma_f32_16x16x32_bf16 v[118:121], v[226:229], v[182:185], v[118:121]
	v_mfma_f32_16x16x32_bf16 v[114:117], v[234:237], v[182:185], v[114:117]
	v_mfma_f32_16x16x32_bf16 v[102:105], v[226:229], v[198:201], v[102:105]
	v_mfma_f32_16x16x32_bf16 v[98:101], v[234:237], v[198:201], v[98:101]
	v_mfma_f32_16x16x32_bf16 v[86:89], v[226:229], v[206:209], v[86:89]
	v_mfma_f32_16x16x32_bf16 v[82:85], v[234:237], v[206:209], v[82:85]
	v_mfma_f32_16x16x32_bf16 v[70:73], v[226:229], v[218:221], v[70:73]
	v_mfma_f32_16x16x32_bf16 v[66:69], v[234:237], v[218:221], v[66:69]
	s_mov_b32 m0, s81
	v_lshl_add_u64 v[238:239], s[68:69], 0, v[146:147]
	s_barrier
	ds_read_b128 v[178:181], v196 offset:16384
	ds_read_b128 v[182:185], v196 offset:17408
	ds_read_b128 v[186:189], v196 offset:18432
	ds_read_b128 v[198:201], v196 offset:19456
	ds_read_b128 v[202:205], v196 offset:20480
	ds_read_b128 v[206:209], v196 offset:21504
	ds_read_b128 v[214:217], v196 offset:22528
	ds_read_b128 v[218:221], v196 offset:23552
	global_load_lds_dwordx4 v[238:239], off
	s_mov_b32 m0, s82
	v_lshl_add_u64 v[240:241], s[68:69], 0, v[148:149]
	global_load_lds_dwordx4 v[240:241], off
	s_barrier
	s_waitcnt lgkmcnt(0)
	v_mfma_f32_16x16x32_bf16 v[62:65], v[130:133], v[178:181], v[62:65]
	v_mfma_f32_16x16x32_bf16 v[58:61], v[138:141], v[178:181], v[58:61]
	v_mfma_f32_16x16x32_bf16 v[46:49], v[130:133], v[186:189], v[46:49]
	v_mfma_f32_16x16x32_bf16 v[42:45], v[138:141], v[186:189], v[42:45]
	v_mfma_f32_16x16x32_bf16 v[30:33], v[130:133], v[202:205], v[30:33]
	v_mfma_f32_16x16x32_bf16 v[26:29], v[138:141], v[202:205], v[26:29]
	v_mfma_f32_16x16x32_bf16 v[14:17], v[130:133], v[214:217], v[14:17]
	v_mfma_f32_16x16x32_bf16 v[10:13], v[138:141], v[214:217], v[10:13]
	v_mfma_f32_16x16x32_bf16 v[62:65], v[134:137], v[182:185], v[62:65]
	v_mfma_f32_16x16x32_bf16 v[58:61], v[142:145], v[182:185], v[58:61]
	v_mfma_f32_16x16x32_bf16 v[46:49], v[134:137], v[198:201], v[46:49]
	v_mfma_f32_16x16x32_bf16 v[42:45], v[142:145], v[198:201], v[42:45]
	v_mfma_f32_16x16x32_bf16 v[30:33], v[134:137], v[206:209], v[30:33]
	v_mfma_f32_16x16x32_bf16 v[26:29], v[142:145], v[206:209], v[26:29]
	v_mfma_f32_16x16x32_bf16 v[14:17], v[134:137], v[218:221], v[14:17]
	v_mfma_f32_16x16x32_bf16 v[10:13], v[142:145], v[218:221], v[10:13]
	s_barrier
; #define PG8_STAGE(bufoff, gbase, voff) do { _Pragma("unroll") for (int _i = 0; _i < 2; ++_i) \
;         __builtin_amdgcn_global_load_lds((const unsigned*)((const char*)(gbase) + (voff)[_i]), (LAS unsigned*)(lds + (bufoff) + ldsw + _i * 8192), 16, 0, 0); } while (0)
; #define PG8_LDA(dst, b, h) do { _Pragma("unroll") for (int m = 0; m < 4; ++m) _Pragma("unroll") for (int k = 0; k < 2; ++k) dst[m][k] = *(const LAS bf16x8*)(lds + PG8_SA(b, h) + aoff + m * 2048 + k * 1024); } while (0)
; #define PG8_LDB(dst, b, h) do { _Pragma("unroll") for (int n = 0; n < 2; ++n) _Pragma("unroll") for (int k = 0; k < 2; ++k) dst[n][k] = *(const LAS bf16x8*)(lds + PG8_SB(b, h) + boff + n * 2048 + k * 1024); } while (0)
; #define PG8_MMA(ai, bj, At, Bt) do { __builtin_amdgcn_s_setprio(1); _Pragma("unroll") for (int m = 0; m < 4; ++m) _Pragma("unroll") for (int n = 0; n < 2; ++n) _Pragma("unroll") for (int k = 0; k < 2; ++k) \
;         acc[ai][bj][m][n] = __builtin_amdgcn_mfma_f32_16x16x32_bf16(Bt[n][k], At[m][k], acc[ai][bj][m][n], 0, 0, 0); __builtin_amdgcn_s_setprio(0); } while (0)
; #define PG8_WAIT_V(n) asm volatile("s_waitcnt vmcnt(" #n ")" ::: "memory")
; #define PG8_WAIT_L(n) asm volatile("s_waitcnt lgkmcnt(" #n ")" ::: "memory")
; #define PG8_BAR __builtin_amdgcn_s_barrier()
; #define PG8_SCHED __builtin_amdgcn_sched_barrier(0)
; template <class Epi>
; DEVI void gemm_phase(LAS unsigned char* lds, const Gemm g, const Epi& E) {
;     ...
;             PG8_STAGE(PG8_SB(0, 1), b2 + hstepB, voffB);
;             PG8_WAIT_V(6); PG8_BAR; PG8_MMA(1, 1, At, B1); PG8_BAR;
;             PG8_LDB(B0, 1, 0); PG8_SCHED; PG8_LDA(At, 1, 0); PG8_STAGE(PG8_SA(0, 1), a2 + hstepA, voffA);
;             PG8_WAIT_L(8); PG8_BAR; PG8_WAIT_L(0); PG8_MMA(0, 0, At, B0); PG8_BAR; PG8_SCHED;
;             PG8_LDB(B1, 1, 1); PG8_STAGE(PG8_SB(1, 0), b3, voffB);
;             PG8_BAR; PG8_WAIT_L(0); PG8_MMA(0, 1, At, B1); PG8_BAR;
;             PG8_LDA(At, 1, 1); PG8_STAGE(PG8_SA(1, 0), a3, voffA);
;             PG8_BAR; PG8_WAIT_L(0); PG8_MMA(1, 0, At, B0); PG8_BAR; PG8_SCHED;
;             PG8_STAGE(PG8_SB(1, 1), b3 + hstepB, voffB);
;             PG8_WAIT_V(6); PG8_BAR; PG8_MMA(1, 1, At, B1); PG8_BAR;
	s_add_u32 s16, s46, 0xb0000
	s_addc_u32 s17, s47, 0
	s_add_i32 s19, s26, s80
	s_mov_b32 m0, s19
	v_lshl_add_u64 v[130:131], s[16:17], 0, v[8:9]
	global_load_lds_dwordx4 v[130:131], off
	s_add_i32 m0, s19, 0x2000
	v_lshl_add_u64 v[130:131], s[16:17], 0, v[150:151]
	global_load_lds_dwordx4 v[130:131], off
	s_waitcnt vmcnt(6)
	s_barrier
	v_mfma_f32_16x16x32_bf16 v[54:57], v[222:225], v[178:181], v[54:57]
	v_mfma_f32_16x16x32_bf16 v[50:53], v[230:233], v[178:181], v[50:53]
	v_mfma_f32_16x16x32_bf16 v[38:41], v[222:225], v[186:189], v[38:41]
	v_mfma_f32_16x16x32_bf16 v[34:37], v[230:233], v[186:189], v[34:37]
	v_mfma_f32_16x16x32_bf16 v[22:25], v[222:225], v[202:205], v[22:25]
	v_mfma_f32_16x16x32_bf16 v[18:21], v[230:233], v[202:205], v[18:21]
	v_mfma_f32_16x16x32_bf16 v[4:7], v[222:225], v[214:217], v[4:7]
	v_mfma_f32_16x16x32_bf16 v[0:3], v[230:233], v[214:217], v[0:3]
	v_mfma_f32_16x16x32_bf16 v[54:57], v[226:229], v[182:185], v[54:57]
	v_mfma_f32_16x16x32_bf16 v[50:53], v[234:237], v[182:185], v[50:53]
	v_mfma_f32_16x16x32_bf16 v[38:41], v[226:229], v[198:201], v[38:41]
	v_mfma_f32_16x16x32_bf16 v[34:37], v[234:237], v[198:201], v[34:37]
	v_mfma_f32_16x16x32_bf16 v[22:25], v[226:229], v[206:209], v[22:25]
	v_mfma_f32_16x16x32_bf16 v[18:21], v[234:237], v[206:209], v[18:21]
	v_mfma_f32_16x16x32_bf16 v[4:7], v[226:229], v[218:221], v[4:7]
	v_mfma_f32_16x16x32_bf16 v[0:3], v[234:237], v[218:221], v[0:3]
	s_add_i32 s19, 0, 0x18000
	v_add_u32_e32 v142, s19, v191
	s_barrier
	ds_read_b128 v[130:133], v142
	ds_read_b128 v[134:137], v142 offset:1024
	ds_read_b128 v[138:141], v142 offset:2048
	ds_read_b128 v[142:145], v142 offset:3072
	s_add_u32 s16, s68, 0xb0000
	s_addc_u32 s17, s69, 0
	s_mov_b32 m0, s83
	v_lshl_add_u64 v[222:223], s[16:17], 0, v[146:147]
	ds_read_b128 v[178:181], v196 offset:32768
	ds_read_b128 v[182:185], v196 offset:33792
	ds_read_b128 v[186:189], v196 offset:34816
	ds_read_b128 v[198:201], v196 offset:35840
	ds_read_b128 v[202:205], v196 offset:36864
	ds_read_b128 v[206:209], v196 offset:37888
	ds_read_b128 v[214:217], v196 offset:38912
	ds_read_b128 v[218:221], v196 offset:39936
	global_load_lds_dwordx4 v[222:223], off
	s_mov_b32 m0, s84
	v_lshl_add_u64 v[222:223], s[16:17], 0, v[148:149]
	global_load_lds_dwordx4 v[222:223], off
	s_waitcnt lgkmcnt(8)
	s_barrier
	s_waitcnt lgkmcnt(0)
	v_mfma_f32_16x16x32_bf16 v[126:129], v[130:133], v[178:181], v[126:129]
	v_mfma_f32_16x16x32_bf16 v[122:125], v[138:141], v[178:181], v[122:125]
	v_mfma_f32_16x16x32_bf16 v[110:113], v[130:133], v[186:189], v[110:113]
	v_mfma_f32_16x16x32_bf16 v[106:109], v[138:141], v[186:189], v[106:109]
	v_mfma_f32_16x16x32_bf16 v[94:97], v[130:133], v[202:205], v[94:97]
	v_mfma_f32_16x16x32_bf16 v[90:93], v[138:141], v[202:205], v[90:93]
	v_mfma_f32_16x16x32_bf16 v[78:81], v[130:133], v[214:217], v[78:81]
	v_mfma_f32_16x16x32_bf16 v[74:77], v[138:141], v[214:217], v[74:77]
	v_mfma_f32_16x16x32_bf16 v[126:129], v[134:137], v[182:185], v[126:129]
	v_mfma_f32_16x16x32_bf16 v[122:125], v[142:145], v[182:185], v[122:125]
	v_mfma_f32_16x16x32_bf16 v[110:113], v[134:137], v[198:201], v[110:113]
	v_mfma_f32_16x16x32_bf16 v[106:109], v[142:145], v[198:201], v[106:109]
	v_mfma_f32_16x16x32_bf16 v[94:97], v[134:137], v[206:209], v[94:97]
	v_mfma_f32_16x16x32_bf16 v[90:93], v[142:145], v[206:209], v[90:93]
	v_mfma_f32_16x16x32_bf16 v[78:81], v[134:137], v[218:221], v[78:81]
	v_mfma_f32_16x16x32_bf16 v[74:77], v[142:145], v[218:221], v[74:77]
	s_barrier
	s_add_i32 s26, 0, 0x1c000
	s_add_i32 s16, s19, s80
	v_add_u32_e32 v197, s26, v191
	v_lshl_add_u64 v[162:163], v[162:163], 0, s[70:71]
	s_mov_b32 m0, s16
	ds_read_b128 v[222:225], v197
	ds_read_b128 v[226:229], v197 offset:1024
	ds_read_b128 v[230:233], v197 offset:2048
	ds_read_b128 v[234:237], v197 offset:3072
	global_load_lds_dwordx4 v[162:163], off
	s_add_i32 m0, s16, 0x2000
	v_lshl_add_u64 v[162:163], v[164:165], 0, s[70:71]
	global_load_lds_dwordx4 v[162:163], off
	s_barrier
	s_waitcnt lgkmcnt(0)
	v_mfma_f32_16x16x32_bf16 v[118:121], v[222:225], v[178:181], v[118:121]
	v_mfma_f32_16x16x32_bf16 v[114:117], v[230:233], v[178:181], v[114:117]
	v_mfma_f32_16x16x32_bf16 v[102:105], v[222:225], v[186:189], v[102:105]
	v_mfma_f32_16x16x32_bf16 v[98:101], v[230:233], v[186:189], v[98:101]
	v_mfma_f32_16x16x32_bf16 v[86:89], v[222:225], v[202:205], v[86:89]
	v_mfma_f32_16x16x32_bf16 v[82:85], v[230:233], v[202:205], v[82:85]
	v_mfma_f32_16x16x32_bf16 v[70:73], v[222:225], v[214:217], v[70:73]
	v_mfma_f32_16x16x32_bf16 v[66:69], v[230:233], v[214:217], v[66:69]
	v_mfma_f32_16x16x32_bf16 v[118:121], v[226:229], v[182:185], v[118:121]
	v_mfma_f32_16x16x32_bf16 v[114:117], v[234:237], v[182:185], v[114:117]
	v_mfma_f32_16x16x32_bf16 v[102:105], v[226:229], v[198:201], v[102:105]
	v_mfma_f32_16x16x32_bf16 v[98:101], v[234:237], v[198:201], v[98:101]
	v_mfma_f32_16x16x32_bf16 v[86:89], v[226:229], v[206:209], v[86:89]
	v_mfma_f32_16x16x32_bf16 v[82:85], v[234:237], v[206:209], v[82:85]
	v_mfma_f32_16x16x32_bf16 v[70:73], v[226:229], v[218:221], v[70:73]
	v_mfma_f32_16x16x32_bf16 v[66:69], v[234:237], v[218:221], v[66:69]
	s_mov_b32 m0, s76
	v_lshl_add_u64 v[162:163], v[238:239], 0, s[70:71]
	s_barrier
	ds_read_b128 v[178:181], v196 offset:49152
	ds_read_b128 v[182:185], v196 offset:50176
	ds_read_b128 v[186:189], v196 offset:51200
	ds_read_b128 v[198:201], v196 offset:52224
	ds_read_b128 v[202:205], v196 offset:53248
	ds_read_b128 v[206:209], v196 offset:54272
	ds_read_b128 v[214:217], v196 offset:55296
	ds_read_b128 v[218:221], v196 offset:56320
	global_load_lds_dwordx4 v[162:163], off
	s_mov_b32 m0, s77
	v_lshl_add_u64 v[162:163], v[240:241], 0, s[70:71]
	global_load_lds_dwordx4 v[162:163], off
	s_barrier
; #define LAS __attribute__((address_space(3)))
;     DEVI f32x4 load(int r, int c) const { const bf16x4 y = *(const bf16x4*)(Y + (size_t)r * DM + c); return (f32x4){bf2f((u16)y[0]), bf2f((u16)y[1]), bf2f((u16)y[2]), bf2f((u16)y[3])}; }
; template <class Epi>
; DEVI void gemm_phase(LAS unsigned char* lds, const Gemm g, const Epi& E) {
;     ...
;             for (int am = 0; am < 4; ++am) {
;                 const int ai = am >> 1, m0 = (am & 1) * 2;
;                 f32x4 pre[2][2][2];
;                 if constexpr (Epi::PRE) {
; #pragma unroll
;                     for (int m = 0; m < 2; ++m)
; #pragma unroll
;                         for (int bj = 0; bj < 2; ++bj)
; #pragma unroll
;                             for (int n = 0; n < 2; ++n) pre[m][bj][n] = E.load(row0 + ai * HALF + (m0 + m) * 16, col0 + bj * HALF + n * NST);
;                 }
; #pragma unroll
;                 for (int mm = 0; mm < 2; ++mm) {
;                     const int m = m0 + mm;
;                     const int r = row0 + ai * HALF + m * 16; float rs = 1.f, part = 0.f;
;                     if constexpr (Epi::RS) rs = rsv[ai * 4 + m];
;                     if constexpr (Epi::PAIR) E.pair8(cur.b, r, cur.pn * HALF + wc * 32 + 8 * fq, acc[ai][0][m][0] * rs, acc[ai][0][m][1] * rs, acc[ai][1][m][0] * rs, acc[ai][1][m][1] * rs);
;                     else
; #pragma unroll
;                     for (int bj = 0; bj < 2; ++bj) {
;                         const int c = col0 + bj * HALF; f32x4 v0 = acc[ai][bj][m][0], v1 = acc[ai][bj][m][1];
;                         if constexpr (Epi::RS) { v0 = v0 * rs; v1 = v1 * rs; }
;                         if constexpr (Epi::PRE) part += E.frag_pre8(cur.b, r, c, v0, v1, pre[mm][bj][0], pre[mm][bj][1]);
;                         else if constexpr (Epi::PERM) E.frag8(cur.b, r, c, v0, v1);
;                         else { E.frag(cur.b, r, c, v0); E.frag(cur.b, r, c + 16, v1); }
;                     }
;                     if constexpr (Epi::SSQ) { part += __shfl_xor(part, 16); part += __shfl_xor(part, 32); if (fq == 0) ((LAS float*)(lds + 131072))[(wr * 4 + wc) * 128 + ai * 64 + m * 16 + fr] = part; }
	s_waitcnt lgkmcnt(0)
	v_mfma_f32_16x16x32_bf16 v[62:65], v[130:133], v[178:181], v[62:65]
	v_mfma_f32_16x16x32_bf16 v[58:61], v[138:141], v[178:181], v[58:61]
	v_mfma_f32_16x16x32_bf16 v[46:49], v[130:133], v[186:189], v[46:49]
	v_mfma_f32_16x16x32_bf16 v[42:45], v[138:141], v[186:189], v[42:45]
	v_mfma_f32_16x16x32_bf16 v[30:33], v[130:133], v[202:205], v[30:33]
	v_mfma_f32_16x16x32_bf16 v[26:29], v[138:141], v[202:205], v[26:29]
	v_mfma_f32_16x16x32_bf16 v[14:17], v[130:133], v[214:217], v[14:17]
	v_mfma_f32_16x16x32_bf16 v[10:13], v[138:141], v[214:217], v[10:13]
	v_mfma_f32_16x16x32_bf16 v[62:65], v[134:137], v[182:185], v[62:65]
	v_mfma_f32_16x16x32_bf16 v[58:61], v[142:145], v[182:185], v[58:61]
	v_mfma_f32_16x16x32_bf16 v[46:49], v[134:137], v[198:201], v[46:49]
	v_mfma_f32_16x16x32_bf16 v[42:45], v[142:145], v[198:201], v[42:45]
	v_mfma_f32_16x16x32_bf16 v[30:33], v[134:137], v[206:209], v[30:33]
	v_mfma_f32_16x16x32_bf16 v[26:29], v[142:145], v[206:209], v[26:29]
	v_mfma_f32_16x16x32_bf16 v[14:17], v[134:137], v[218:221], v[14:17]
	v_mfma_f32_16x16x32_bf16 v[10:13], v[142:145], v[218:221], v[10:13]
	s_barrier
	s_add_u32 s16, s46, 0xb0080
	s_addc_u32 s17, s47, 0
	s_add_i32 s19, s26, s80
	s_mov_b32 m0, s19
	v_lshl_add_u64 v[130:131], s[16:17], 0, v[8:9]
	global_load_lds_dwordx4 v[130:131], off
	s_add_i32 m0, s19, 0x2000
	v_lshl_add_u64 v[130:131], s[16:17], 0, v[150:151]
	global_load_lds_dwordx4 v[130:131], off
	s_waitcnt vmcnt(6)
	s_barrier
	v_mfma_f32_16x16x32_bf16 v[54:57], v[222:225], v[178:181], v[54:57]
	v_mfma_f32_16x16x32_bf16 v[50:53], v[230:233], v[178:181], v[50:53]
	v_mfma_f32_16x16x32_bf16 v[38:41], v[222:225], v[186:189], v[38:41]
	v_mfma_f32_16x16x32_bf16 v[34:37], v[230:233], v[186:189], v[34:37]
	v_mfma_f32_16x16x32_bf16 v[22:25], v[222:225], v[202:205], v[22:25]
	v_mfma_f32_16x16x32_bf16 v[18:21], v[230:233], v[202:205], v[18:21]
	v_mfma_f32_16x16x32_bf16 v[4:7], v[222:225], v[214:217], v[4:7]
	v_mfma_f32_16x16x32_bf16 v[0:3], v[230:233], v[214:217], v[0:3]
	v_mfma_f32_16x16x32_bf16 v[54:57], v[226:229], v[182:185], v[54:57]
	v_mfma_f32_16x16x32_bf16 v[50:53], v[234:237], v[182:185], v[50:53]
	v_mfma_f32_16x16x32_bf16 v[38:41], v[226:229], v[198:201], v[38:41]
	v_mfma_f32_16x16x32_bf16 v[34:37], v[234:237], v[198:201], v[34:37]
	v_mfma_f32_16x16x32_bf16 v[22:25], v[226:229], v[206:209], v[22:25]
	v_mfma_f32_16x16x32_bf16 v[18:21], v[234:237], v[206:209], v[18:21]
	v_mfma_f32_16x16x32_bf16 v[4:7], v[226:229], v[218:221], v[4:7]
	v_mfma_f32_16x16x32_bf16 v[0:3], v[234:237], v[218:221], v[0:3]
	s_add_i32 s18, s18, 2
	s_add_u32 s1, s1, 0x100
	s_addc_u32 s13, s13, 0
	s_cmp_gt_u32 s18, 41
	s_mov_b64 s[16:17], s[36:37]
	s_barrier
	s_cbranch_scc0 .LBB0_1747
	s_setprio 0
	s_lshl_b32 s0, s0, 8
	v_add_u32_e32 v182, s0, v190
	v_lshl_or_b32 v180, s12, 8, v195
	v_ashrrev_i32_e32 v183, 31, v182
	v_lshlrev_b64 v[130:131], 12, v[182:183]
	v_ashrrev_i32_e32 v181, 31, v180
	v_lshl_add_u64 v[130:131], s[30:31], 0, v[130:131]
	v_lshlrev_b64 v[184:185], 2, v[180:181]
	v_lshl_add_u64 v[162:163], v[130:131], 0, v[184:185]
	global_load_dwordx4 v[200:203], v[162:163], off nt
	global_load_dwordx4 v[204:207], v[162:163], off offset:16 nt
	global_load_dwordx4 v[214:217], v[162:163], off offset:512 nt
	global_load_dwordx4 v[218:221], v[162:163], off offset:528 nt
	v_or_b32_e32 v188, 16, v182
	v_ashrrev_i32_e32 v189, 31, v188
	v_lshlrev_b64 v[130:131], 12, v[188:189]
	v_lshl_add_u64 v[130:131], s[30:31], 0, v[130:131]
	v_lshl_add_u64 v[186:187], v[130:131], 0, v[184:185]
	global_load_dwordx4 v[138:141], v[186:187], off offset:16 nt
	global_load_dwordx4 v[142:145], v[186:187], off nt
	global_load_dwordx4 v[130:133], v[186:187], off offset:528 nt
	global_load_dwordx4 v[134:137], v[186:187], off offset:512 nt
	v_and_b32_e32 v165, 64, v155
	v_xor_b32_e32 v164, 16, v155
	v_add_u32_e32 v165, 64, v165
	v_xor_b32_e32 v179, 32, v155
	v_cmp_lt_i32_e32 vcc, v164, v165
	v_or_b32_e32 v178, 0x80, v180
	s_waitcnt vmcnt(0)
	v_pk_add_f32 v[128:129], v[128:129], v[202:203]
	v_cndmask_b32_e32 v164, v155, v164, vcc
	v_cmp_lt_i32_e32 vcc, v179, v165
	v_lshlrev_b32_e32 v198, 2, v164
	v_pk_add_f32 v[126:127], v[126:127], v[200:201]
	v_cndmask_b32_e32 v165, v155, v179, vcc
	v_lshlrev_b32_e32 v197, 2, v165
	v_lshlrev_b64 v[164:165], 10, v[182:183]
	v_pk_add_f32 v[124:125], v[124:125], v[206:207]
	v_pk_add_f32 v[122:123], v[122:123], v[204:205]
	v_pk_add_f32 v[120:121], v[120:121], v[216:217]
	v_pk_add_f32 v[118:119], v[118:119], v[214:215]
	v_pk_add_f32 v[202:203], v[116:117], v[220:221]
	v_pk_add_f32 v[200:201], v[114:115], v[218:219]
	v_lshl_add_u64 v[208:209], v[164:165], 0, v[180:181]
	global_store_dwordx4 v[162:163], v[126:129], off nt
	global_store_dwordx4 v[162:163], v[122:125], off offset:16 nt
	v_cvt_pk_bf16_f32 v114, v126, v127
	v_cvt_pk_bf16_f32 v115, v128, v129
	v_cvt_pk_bf16_f32 v116, v122, v123
	v_cvt_pk_bf16_f32 v117, v124, v125
	v_mul_f32_e32 v127, v127, v127
	v_mul_f32_e32 v129, v129, v129
	v_mul_f32_e32 v123, v123, v123
	v_mul_f32_e32 v125, v125, v125
	v_mul_f32_e32 v183, v119, v119
	v_mul_f32_e32 v199, v121, v121
	v_mul_f32_e32 v204, v201, v201
	v_mul_f32_e32 v205, v203, v203
	v_lshl_add_u64 v[208:209], v[208:209], 1, s[24:25]
	v_fmac_f32_e32 v127, v126, v126
	v_fmac_f32_e32 v129, v128, v128
	v_fmac_f32_e32 v123, v122, v122
	v_fmac_f32_e32 v125, v124, v124
	v_fmac_f32_e32 v183, v118, v118
	v_fmac_f32_e32 v199, v120, v120
	v_fmac_f32_e32 v204, v200, v200
	v_fmac_f32_e32 v205, v202, v202
	global_store_dwordx4 v[208:209], v[114:117], off
	v_ashrrev_i32_e32 v179, 31, v178
	v_lshl_add_u64 v[164:165], v[164:165], 0, v[178:179]
	v_add_f32_e32 v114, v127, v129
	v_add_f32_e32 v115, v123, v125
	v_add_f32_e32 v116, v183, v199
	v_add_f32_e32 v117, v204, v205
	v_add_f32_e32 v114, v114, v115
	v_add_f32_e32 v115, v116, v117
	v_add_f32_e32 v114, v114, v115
	ds_bpermute_b32 v115, v198, v114
	global_store_dwordx4 v[162:163], v[118:121], off offset:512 nt
	global_store_dwordx4 v[162:163], v[200:203], off offset:528 nt
	v_cvt_pk_bf16_f32 v116, v118, v119
	v_cvt_pk_bf16_f32 v117, v120, v121
	v_cvt_pk_bf16_f32 v118, v200, v201
	s_waitcnt lgkmcnt(0)
	v_add_f32_e32 v114, v114, v115
	ds_bpermute_b32 v115, v197, v114
	v_cvt_pk_bf16_f32 v119, v202, v203
	v_lshl_add_u64 v[120:121], v[164:165], 1, s[24:25]
	global_store_dwordx4 v[120:121], v[116:119], off
	s_and_saveexec_b64 s[16:17], s[2:3]
	s_cbranch_execz .LBB0_1750
	s_waitcnt lgkmcnt(0)
	v_add_f32_e32 v114, v114, v115
	ds_write_b32 v192, v114

; #define LAS __attribute__((address_space(3)))
;     DEVI f32x4 load(int r, int c) const { const bf16x4 y = *(const bf16x4*)(Y + (size_t)r * DM + c); return (f32x4){bf2f((u16)y[0]), bf2f((u16)y[1]), bf2f((u16)y[2]), bf2f((u16)y[3])}; }
; template <class Epi>
; DEVI void gemm_phase(LAS unsigned char* lds, const Gemm g, const Epi& E) {
;     ...
;             for (int am = 0; am < 4; ++am) {
;                 const int ai = am >> 1, m0 = (am & 1) * 2;
;                 f32x4 pre[2][2][2];
;                 if constexpr (Epi::PRE) {
; #pragma unroll
;                     for (int m = 0; m < 2; ++m)
; #pragma unroll
;                         for (int bj = 0; bj < 2; ++bj)
; #pragma unroll
;                             for (int n = 0; n < 2; ++n) pre[m][bj][n] = E.load(row0 + ai * HALF + (m0 + m) * 16, col0 + bj * HALF + n * NST);
;                 }
; #pragma unroll
;                 for (int mm = 0; mm < 2; ++mm) {
;                     const int m = m0 + mm;
;                     const int r = row0 + ai * HALF + m * 16; float rs = 1.f, part = 0.f;
;                     if constexpr (Epi::RS) rs = rsv[ai * 4 + m];
;                     if constexpr (Epi::PAIR) E.pair8(cur.b, r, cur.pn * HALF + wc * 32 + 8 * fq, acc[ai][0][m][0] * rs, acc[ai][0][m][1] * rs, acc[ai][1][m][0] * rs, acc[ai][1][m][1] * rs);
;                     else
; #pragma unroll
;                     for (int bj = 0; bj < 2; ++bj) {
;                         const int c = col0 + bj * HALF; f32x4 v0 = acc[ai][bj][m][0], v1 = acc[ai][bj][m][1];
;                         if constexpr (Epi::RS) { v0 = v0 * rs; v1 = v1 * rs; }
;                         if constexpr (Epi::PRE) part += E.frag_pre8(cur.b, r, c, v0, v1, pre[mm][bj][0], pre[mm][bj][1]);
;                         else if constexpr (Epi::PERM) E.frag8(cur.b, r, c, v0, v1);
;                         else { E.frag(cur.b, r, c, v0); E.frag(cur.b, r, c + 16, v1); }
;                     }
;                     if constexpr (Epi::SSQ) { part += __shfl_xor(part, 16); part += __shfl_xor(part, 32); if (fq == 0) ((LAS float*)(lds + 131072))[(wr * 4 + wc) * 128 + ai * 64 + m * 16 + fr] = part; }
.LBB0_1752:
	s_or_b64 exec, exec, s[16:17]
	v_or_b32_e32 v134, 32, v182
	v_ashrrev_i32_e32 v135, 31, v134
	s_waitcnt lgkmcnt(0)
	v_lshlrev_b64 v[98:99], 12, v[134:135]
	v_lshl_add_u64 v[98:99], s[30:31], 0, v[98:99]
	v_lshl_add_u64 v[136:137], v[98:99], 0, v[184:185]
	global_load_dwordx4 v[118:121], v[136:137], off nt
	global_load_dwordx4 v[122:125], v[136:137], off offset:16 nt
	global_load_dwordx4 v[126:129], v[136:137], off offset:512 nt
	global_load_dwordx4 v[130:133], v[136:137], off offset:528 nt
	v_or_b32_e32 v116, 48, v182
	v_ashrrev_i32_e32 v117, 31, v116
	v_lshlrev_b64 v[98:99], 12, v[116:117]
	v_lshl_add_u64 v[98:99], s[30:31], 0, v[98:99]
	v_lshl_add_u64 v[114:115], v[98:99], 0, v[184:185]
	global_load_dwordx4 v[106:109], v[114:115], off offset:16 nt
	global_load_dwordx4 v[110:113], v[114:115], off nt
	global_load_dwordx4 v[98:101], v[114:115], off offset:528 nt
	global_load_dwordx4 v[102:105], v[114:115], off offset:512 nt
	v_lshlrev_b64 v[134:135], 10, v[134:135]
	v_lshl_add_u64 v[138:139], v[134:135], 0, v[180:181]
	v_lshl_add_u64 v[138:139], v[138:139], 1, s[24:25]
	v_lshl_add_u64 v[134:135], v[134:135], 0, v[178:179]
	s_waitcnt vmcnt(7)
	v_pk_add_f32 v[96:97], v[96:97], v[120:121]
	v_pk_add_f32 v[94:95], v[94:95], v[118:119]
	s_waitcnt vmcnt(6)
	v_pk_add_f32 v[92:93], v[92:93], v[124:125]
	v_pk_add_f32 v[90:91], v[90:91], v[122:123]
	s_waitcnt vmcnt(5)
	v_pk_add_f32 v[88:89], v[88:89], v[128:129]
	v_pk_add_f32 v[86:87], v[86:87], v[126:127]
	s_waitcnt vmcnt(4)
	v_pk_add_f32 v[120:121], v[84:85], v[132:133]
	v_pk_add_f32 v[118:119], v[82:83], v[130:131]
	global_store_dwordx4 v[136:137], v[94:97], off nt
	global_store_dwordx4 v[136:137], v[90:93], off offset:16 nt
	v_cvt_pk_bf16_f32 v82, v94, v95
	v_cvt_pk_bf16_f32 v83, v96, v97
	v_cvt_pk_bf16_f32 v84, v90, v91
	v_cvt_pk_bf16_f32 v85, v92, v93
	v_mul_f32_e32 v95, v95, v95
	v_mul_f32_e32 v97, v97, v97
	v_mul_f32_e32 v91, v91, v91
	v_mul_f32_e32 v93, v93, v93
	v_mul_f32_e32 v122, v87, v87
	v_mul_f32_e32 v123, v89, v89
	v_mul_f32_e32 v124, v119, v119
	v_mul_f32_e32 v125, v121, v121
	v_fmac_f32_e32 v95, v94, v94
	v_fmac_f32_e32 v97, v96, v96
	v_fmac_f32_e32 v91, v90, v90
	v_fmac_f32_e32 v93, v92, v92
	v_fmac_f32_e32 v122, v86, v86
	v_fmac_f32_e32 v123, v88, v88
	v_fmac_f32_e32 v124, v118, v118
	v_fmac_f32_e32 v125, v120, v120
	global_store_dwordx4 v[138:139], v[82:85], off
	global_store_dwordx4 v[136:137], v[86:89], off offset:512 nt
	global_store_dwordx4 v[136:137], v[118:121], off offset:528 nt
	v_add_f32_e32 v82, v95, v97
	v_add_f32_e32 v83, v91, v93
	v_add_f32_e32 v84, v122, v123
	v_add_f32_e32 v85, v124, v125
	v_add_f32_e32 v82, v82, v83
	v_add_f32_e32 v83, v84, v85
	v_add_f32_e32 v82, v82, v83
	ds_bpermute_b32 v83, v198, v82
	v_cvt_pk_bf16_f32 v84, v86, v87
	v_cvt_pk_bf16_f32 v85, v88, v89
	v_cvt_pk_bf16_f32 v86, v118, v119
	v_cvt_pk_bf16_f32 v87, v120, v121
	s_waitcnt lgkmcnt(0)
	v_add_f32_e32 v82, v82, v83
	ds_bpermute_b32 v83, v197, v82
	v_lshl_add_u64 v[88:89], v[134:135], 1, s[24:25]
	global_store_dwordx4 v[88:89], v[84:87], off
	s_and_saveexec_b64 s[16:17], s[2:3]
	s_cbranch_execz .LBB0_1754
	s_waitcnt lgkmcnt(0)
	v_add_f32_e32 v82, v82, v83
	ds_write_b32 v192, v82 offset:128

; #define LAS __attribute__((address_space(3)))
;     DEVI f32x4 load(int r, int c) const { const bf16x4 y = *(const bf16x4*)(Y + (size_t)r * DM + c); return (f32x4){bf2f((u16)y[0]), bf2f((u16)y[1]), bf2f((u16)y[2]), bf2f((u16)y[3])}; }
; template <class Epi>
; DEVI void gemm_phase(LAS unsigned char* lds, const Gemm g, const Epi& E) {
;     ...
;             for (int am = 0; am < 4; ++am) {
;                 const int ai = am >> 1, m0 = (am & 1) * 2;
;                 f32x4 pre[2][2][2];
;                 if constexpr (Epi::PRE) {
; #pragma unroll
;                     for (int m = 0; m < 2; ++m)
; #pragma unroll
;                         for (int bj = 0; bj < 2; ++bj)
; #pragma unroll
;                             for (int n = 0; n < 2; ++n) pre[m][bj][n] = E.load(row0 + ai * HALF + (m0 + m) * 16, col0 + bj * HALF + n * NST);
;                 }
; #pragma unroll
;                 for (int mm = 0; mm < 2; ++mm) {
;                     const int m = m0 + mm;
;                     const int r = row0 + ai * HALF + m * 16; float rs = 1.f, part = 0.f;
;                     if constexpr (Epi::RS) rs = rsv[ai * 4 + m];
;                     if constexpr (Epi::PAIR) E.pair8(cur.b, r, cur.pn * HALF + wc * 32 + 8 * fq, acc[ai][0][m][0] * rs, acc[ai][0][m][1] * rs, acc[ai][1][m][0] * rs, acc[ai][1][m][1] * rs);
;                     else
; #pragma unroll
;                     for (int bj = 0; bj < 2; ++bj) {
;                         const int c = col0 + bj * HALF; f32x4 v0 = acc[ai][bj][m][0], v1 = acc[ai][bj][m][1];
;                         if constexpr (Epi::RS) { v0 = v0 * rs; v1 = v1 * rs; }
;                         if constexpr (Epi::PRE) part += E.frag_pre8(cur.b, r, c, v0, v1, pre[mm][bj][0], pre[mm][bj][1]);
;                         else if constexpr (Epi::PERM) E.frag8(cur.b, r, c, v0, v1);
;                         else { E.frag(cur.b, r, c, v0); E.frag(cur.b, r, c + 16, v1); }
;                     }
;                     if constexpr (Epi::SSQ) { part += __shfl_xor(part, 16); part += __shfl_xor(part, 32); if (fq == 0) ((LAS float*)(lds + 131072))[(wr * 4 + wc) * 128 + ai * 64 + m * 16 + fr] = part; }
.LBB0_1756:
	s_or_b64 exec, exec, s[16:17]
	v_add_u32_e32 v102, 0x80, v182
	v_ashrrev_i32_e32 v103, 31, v102
	s_waitcnt lgkmcnt(0)
	v_lshlrev_b64 v[66:67], 12, v[102:103]
	v_lshl_add_u64 v[66:67], s[30:31], 0, v[66:67]
	v_lshl_add_u64 v[104:105], v[66:67], 0, v[184:185]
	global_load_dwordx4 v[86:89], v[104:105], off nt
	global_load_dwordx4 v[90:93], v[104:105], off offset:16 nt
	global_load_dwordx4 v[94:97], v[104:105], off offset:512 nt
	global_load_dwordx4 v[98:101], v[104:105], off offset:528 nt
	v_add_u32_e32 v84, 0x90, v182
	v_ashrrev_i32_e32 v85, 31, v84
	v_lshlrev_b64 v[66:67], 12, v[84:85]
	v_lshl_add_u64 v[66:67], s[30:31], 0, v[66:67]
	v_lshl_add_u64 v[82:83], v[66:67], 0, v[184:185]
	global_load_dwordx4 v[74:77], v[82:83], off offset:16 nt
	global_load_dwordx4 v[78:81], v[82:83], off nt
	global_load_dwordx4 v[66:69], v[82:83], off offset:528 nt
	global_load_dwordx4 v[70:73], v[82:83], off offset:512 nt
	v_lshlrev_b64 v[102:103], 10, v[102:103]
	v_lshl_add_u64 v[106:107], v[102:103], 0, v[180:181]
	v_lshl_add_u64 v[106:107], v[106:107], 1, s[24:25]
	v_lshl_add_u64 v[102:103], v[102:103], 0, v[178:179]
	s_waitcnt vmcnt(7)
	v_pk_add_f32 v[64:65], v[64:65], v[88:89]
	v_pk_add_f32 v[62:63], v[62:63], v[86:87]
	s_waitcnt vmcnt(6)
	v_pk_add_f32 v[60:61], v[60:61], v[92:93]
	v_pk_add_f32 v[58:59], v[58:59], v[90:91]
	s_waitcnt vmcnt(5)
	v_pk_add_f32 v[56:57], v[56:57], v[96:97]
	v_pk_add_f32 v[54:55], v[54:55], v[94:95]
	s_waitcnt vmcnt(4)
	v_pk_add_f32 v[88:89], v[52:53], v[100:101]
	v_pk_add_f32 v[86:87], v[50:51], v[98:99]
	global_store_dwordx4 v[104:105], v[62:65], off nt
	global_store_dwordx4 v[104:105], v[58:61], off offset:16 nt
	v_cvt_pk_bf16_f32 v50, v62, v63
	v_cvt_pk_bf16_f32 v51, v64, v65
	v_cvt_pk_bf16_f32 v52, v58, v59
	v_cvt_pk_bf16_f32 v53, v60, v61
	v_mul_f32_e32 v63, v63, v63
	v_mul_f32_e32 v65, v65, v65
	v_mul_f32_e32 v59, v59, v59
	v_mul_f32_e32 v61, v61, v61
	v_mul_f32_e32 v90, v55, v55
	v_mul_f32_e32 v91, v57, v57
	v_mul_f32_e32 v92, v87, v87
	v_mul_f32_e32 v93, v89, v89
	v_fmac_f32_e32 v63, v62, v62
	v_fmac_f32_e32 v65, v64, v64
	v_fmac_f32_e32 v59, v58, v58
	v_fmac_f32_e32 v61, v60, v60
	v_fmac_f32_e32 v90, v54, v54
	v_fmac_f32_e32 v91, v56, v56
	v_fmac_f32_e32 v92, v86, v86
	v_fmac_f32_e32 v93, v88, v88
	global_store_dwordx4 v[106:107], v[50:53], off
	global_store_dwordx4 v[104:105], v[54:57], off offset:512 nt
	global_store_dwordx4 v[104:105], v[86:89], off offset:528 nt
	v_add_f32_e32 v50, v63, v65
	v_add_f32_e32 v51, v59, v61
	v_add_f32_e32 v52, v90, v91
	v_add_f32_e32 v53, v92, v93
	v_add_f32_e32 v50, v50, v51
	v_add_f32_e32 v51, v52, v53
	v_add_f32_e32 v50, v50, v51
	ds_bpermute_b32 v51, v198, v50
	v_cvt_pk_bf16_f32 v52, v54, v55
	v_cvt_pk_bf16_f32 v53, v56, v57
	v_cvt_pk_bf16_f32 v54, v86, v87
	v_cvt_pk_bf16_f32 v55, v88, v89
	s_waitcnt lgkmcnt(0)
	v_add_f32_e32 v50, v50, v51
	ds_bpermute_b32 v51, v197, v50
	v_lshl_add_u64 v[56:57], v[102:103], 1, s[24:25]
	global_store_dwordx4 v[56:57], v[52:55], off
	s_and_saveexec_b64 s[16:17], s[2:3]
	s_cbranch_execz .LBB0_1758
	s_waitcnt lgkmcnt(0)
	v_add_f32_e32 v50, v50, v51
	ds_write_b32 v192, v50 offset:256

; #define LAS __attribute__((address_space(3)))
;     DEVI f32x4 load(int r, int c) const { const bf16x4 y = *(const bf16x4*)(Y + (size_t)r * DM + c); return (f32x4){bf2f((u16)y[0]), bf2f((u16)y[1]), bf2f((u16)y[2]), bf2f((u16)y[3])}; }
; template <class Epi>
; DEVI void gemm_phase(LAS unsigned char* lds, const Gemm g, const Epi& E) {
;     ...
;             for (int am = 0; am < 4; ++am) {
;                 const int ai = am >> 1, m0 = (am & 1) * 2;
;                 f32x4 pre[2][2][2];
;                 if constexpr (Epi::PRE) {
; #pragma unroll
;                     for (int m = 0; m < 2; ++m)
; #pragma unroll
;                         for (int bj = 0; bj < 2; ++bj)
; #pragma unroll
;                             for (int n = 0; n < 2; ++n) pre[m][bj][n] = E.load(row0 + ai * HALF + (m0 + m) * 16, col0 + bj * HALF + n * NST);
;                 }
; #pragma unroll
;                 for (int mm = 0; mm < 2; ++mm) {
;                     const int m = m0 + mm;
;                     const int r = row0 + ai * HALF + m * 16; float rs = 1.f, part = 0.f;
;                     if constexpr (Epi::RS) rs = rsv[ai * 4 + m];
;                     if constexpr (Epi::PAIR) E.pair8(cur.b, r, cur.pn * HALF + wc * 32 + 8 * fq, acc[ai][0][m][0] * rs, acc[ai][0][m][1] * rs, acc[ai][1][m][0] * rs, acc[ai][1][m][1] * rs);
;                     else
; #pragma unroll
;                     for (int bj = 0; bj < 2; ++bj) {
;                         const int c = col0 + bj * HALF; f32x4 v0 = acc[ai][bj][m][0], v1 = acc[ai][bj][m][1];
;                         if constexpr (Epi::RS) { v0 = v0 * rs; v1 = v1 * rs; }
;                         if constexpr (Epi::PRE) part += E.frag_pre8(cur.b, r, c, v0, v1, pre[mm][bj][0], pre[mm][bj][1]);
;                         else if constexpr (Epi::PERM) E.frag8(cur.b, r, c, v0, v1);
;                         else { E.frag(cur.b, r, c, v0); E.frag(cur.b, r, c + 16, v1); }
;                     }
;                     if constexpr (Epi::SSQ) { part += __shfl_xor(part, 16); part += __shfl_xor(part, 32); if (fq == 0) ((LAS float*)(lds + 131072))[(wr * 4 + wc) * 128 + ai * 64 + m * 16 + fr] = part; }
.LBB0_1760:
	s_or_b64 exec, exec, s[16:17]
	v_add_u32_e32 v70, 0xa0, v182
	v_ashrrev_i32_e32 v71, 31, v70
	s_waitcnt lgkmcnt(0)
	v_lshlrev_b64 v[34:35], 12, v[70:71]
	v_lshl_add_u64 v[34:35], s[30:31], 0, v[34:35]
	v_lshl_add_u64 v[72:73], v[34:35], 0, v[184:185]
	global_load_dwordx4 v[54:57], v[72:73], off nt
	global_load_dwordx4 v[58:61], v[72:73], off offset:16 nt
	global_load_dwordx4 v[62:65], v[72:73], off offset:512 nt
	global_load_dwordx4 v[66:69], v[72:73], off offset:528 nt
	v_add_u32_e32 v52, 0xb0, v182
	v_ashrrev_i32_e32 v53, 31, v52
	v_lshlrev_b64 v[34:35], 12, v[52:53]
	v_lshl_add_u64 v[34:35], s[30:31], 0, v[34:35]
	v_lshl_add_u64 v[50:51], v[34:35], 0, v[184:185]
	global_load_dwordx4 v[42:45], v[50:51], off offset:16 nt
	global_load_dwordx4 v[46:49], v[50:51], off nt
	global_load_dwordx4 v[34:37], v[50:51], off offset:528 nt
	global_load_dwordx4 v[38:41], v[50:51], off offset:512 nt
	v_lshlrev_b64 v[70:71], 10, v[70:71]
	v_lshl_add_u64 v[74:75], v[70:71], 0, v[180:181]
	v_lshl_add_u64 v[74:75], v[74:75], 1, s[24:25]
	v_lshl_add_u64 v[70:71], v[70:71], 0, v[178:179]
	s_waitcnt vmcnt(7)
	v_pk_add_f32 v[32:33], v[32:33], v[56:57]
	v_pk_add_f32 v[30:31], v[30:31], v[54:55]
	s_waitcnt vmcnt(6)
	v_pk_add_f32 v[28:29], v[28:29], v[60:61]
	v_pk_add_f32 v[26:27], v[26:27], v[58:59]
	s_waitcnt vmcnt(5)
	v_pk_add_f32 v[24:25], v[24:25], v[64:65]
	v_pk_add_f32 v[22:23], v[22:23], v[62:63]
	s_waitcnt vmcnt(4)
	v_pk_add_f32 v[56:57], v[20:21], v[68:69]
	v_pk_add_f32 v[54:55], v[18:19], v[66:67]
	global_store_dwordx4 v[72:73], v[30:33], off nt
	global_store_dwordx4 v[72:73], v[26:29], off offset:16 nt
	v_cvt_pk_bf16_f32 v18, v30, v31
	v_cvt_pk_bf16_f32 v19, v32, v33
	v_cvt_pk_bf16_f32 v20, v26, v27
	v_cvt_pk_bf16_f32 v21, v28, v29
	v_mul_f32_e32 v31, v31, v31
	v_mul_f32_e32 v33, v33, v33
	v_mul_f32_e32 v27, v27, v27
	v_mul_f32_e32 v29, v29, v29
	v_mul_f32_e32 v58, v23, v23
	v_mul_f32_e32 v59, v25, v25
	v_mul_f32_e32 v60, v55, v55
	v_mul_f32_e32 v61, v57, v57
	v_fmac_f32_e32 v31, v30, v30
	v_fmac_f32_e32 v33, v32, v32
	v_fmac_f32_e32 v27, v26, v26
	v_fmac_f32_e32 v29, v28, v28
	v_fmac_f32_e32 v58, v22, v22
	v_fmac_f32_e32 v59, v24, v24
	v_fmac_f32_e32 v60, v54, v54
	v_fmac_f32_e32 v61, v56, v56
	global_store_dwordx4 v[74:75], v[18:21], off
	global_store_dwordx4 v[72:73], v[22:25], off offset:512 nt
	global_store_dwordx4 v[72:73], v[54:57], off offset:528 nt
	v_add_f32_e32 v18, v31, v33
	v_add_f32_e32 v19, v27, v29
	v_add_f32_e32 v20, v58, v59
	v_add_f32_e32 v21, v60, v61
	v_add_f32_e32 v18, v18, v19
	v_add_f32_e32 v19, v20, v21
	v_add_f32_e32 v18, v18, v19
	ds_bpermute_b32 v19, v198, v18
	v_cvt_pk_bf16_f32 v20, v22, v23
	v_cvt_pk_bf16_f32 v21, v24, v25
	v_cvt_pk_bf16_f32 v22, v54, v55
	v_cvt_pk_bf16_f32 v23, v56, v57
	s_waitcnt lgkmcnt(0)
	v_add_f32_e32 v18, v18, v19
	ds_bpermute_b32 v19, v197, v18
	v_lshl_add_u64 v[24:25], v[70:71], 1, s[24:25]
	global_store_dwordx4 v[24:25], v[20:23], off
	s_and_saveexec_b64 s[16:17], s[2:3]
	s_cbranch_execz .LBB0_1762
	s_waitcnt lgkmcnt(0)
	v_add_f32_e32 v18, v18, v19
	ds_write_b32 v192, v18 offset:384
